# GEMM loop: 4/4 DMA split + LDS-DMA issued in saddr form (drops the 64-bit VALU address adds from the load segments)
# baseline (speedup 1.0000x reference)
.LBB0_176:
	s_mov_b32 m0, s55
	s_nop 0
	global_load_lds_dwordx4 v194, s[100:101]
	s_mov_b32 m0, s67
	s_nop 0
	global_load_lds_dwordx4 v196, s[100:101]
	v_add_u32_e32 v130, 0x10000, v243
	v_add_u32_e32 v142, 0x14000, v243
	ds_read_b128 v[146:149], v130
	ds_read_b128 v[150:153], v130 offset:1024
	ds_read_b128 v[154:157], v130 offset:2048
	ds_read_b128 v[158:161], v130 offset:3072
	ds_read_b128 v[130:133], v142
	ds_read_b128 v[134:137], v142 offset:1024
	ds_read_b128 v[138:141], v142 offset:2048
	ds_read_b128 v[142:145], v142 offset:3072
	v_lshl_add_u64 v[246:247], v[234:235], 0, s[80:81]
	s_add_i32 m0, s8, 0xc000
	s_waitcnt lgkmcnt(0)
	ds_read_b128 v[174:177], v244
	ds_read_b128 v[190:193], v244 offset:1024
	ds_read_b128 v[170:173], v244 offset:2048
	ds_read_b128 v[186:189], v244 offset:3072
	ds_read_b128 v[166:169], v244 offset:4096
	ds_read_b128 v[182:185], v244 offset:5120
	ds_read_b128 v[162:165], v244 offset:6144
	ds_read_b128 v[178:181], v244 offset:7168
	global_load_lds_dwordx4 v[246:247], off
	v_lshl_add_u64 v[246:247], v[236:237], 0, s[80:81]
	s_add_i32 m0, s8, 0xe000
	s_nop 0
	global_load_lds_dwordx4 v[246:247], off
	s_waitcnt vmcnt(8)
	s_waitcnt lgkmcnt(0)
	s_barrier
	s_setprio 1
	s_waitcnt lgkmcnt(0)
	v_mfma_f32_16x16x32_bf16 v[118:121], v[146:149], v[174:177], v[118:121]
	v_mfma_f32_16x16x32_bf16 v[126:129], v[154:157], v[174:177], v[126:129]
	v_mfma_f32_16x16x32_bf16 v[102:105], v[146:149], v[170:173], v[102:105]
	v_mfma_f32_16x16x32_bf16 v[110:113], v[154:157], v[170:173], v[110:113]
	v_mfma_f32_16x16x32_bf16 v[86:89], v[146:149], v[166:169], v[86:89]
	v_mfma_f32_16x16x32_bf16 v[94:97], v[154:157], v[166:169], v[94:97]
	v_mfma_f32_16x16x32_bf16 v[70:73], v[146:149], v[162:165], v[70:73]
	v_mfma_f32_16x16x32_bf16 v[78:81], v[154:157], v[162:165], v[78:81]
	v_mfma_f32_16x16x32_bf16 v[118:121], v[150:153], v[190:193], v[118:121]
	v_mfma_f32_16x16x32_bf16 v[126:129], v[158:161], v[190:193], v[126:129]
	v_mfma_f32_16x16x32_bf16 v[102:105], v[150:153], v[186:189], v[102:105]
	v_mfma_f32_16x16x32_bf16 v[110:113], v[158:161], v[186:189], v[110:113]
	v_mfma_f32_16x16x32_bf16 v[86:89], v[150:153], v[182:185], v[86:89]
	v_mfma_f32_16x16x32_bf16 v[94:97], v[158:161], v[182:185], v[94:97]
	v_mfma_f32_16x16x32_bf16 v[70:73], v[150:153], v[178:181], v[70:73]
	v_mfma_f32_16x16x32_bf16 v[78:81], v[158:161], v[178:181], v[78:81]
	s_setprio 0
	s_setprio 1
	v_mfma_f32_16x16x32_bf16 v[122:125], v[130:133], v[174:177], v[122:125]
	v_mfma_f32_16x16x32_bf16 v[114:117], v[138:141], v[174:177], v[114:117]
	v_mfma_f32_16x16x32_bf16 v[106:109], v[130:133], v[170:173], v[106:109]
	v_mfma_f32_16x16x32_bf16 v[98:101], v[138:141], v[170:173], v[98:101]
	v_mfma_f32_16x16x32_bf16 v[90:93], v[130:133], v[166:169], v[90:93]
	v_mfma_f32_16x16x32_bf16 v[82:85], v[138:141], v[166:169], v[82:85]
	v_mfma_f32_16x16x32_bf16 v[74:77], v[130:133], v[162:165], v[74:77]
	v_mfma_f32_16x16x32_bf16 v[66:69], v[138:141], v[162:165], v[66:69]
	v_mfma_f32_16x16x32_bf16 v[122:125], v[134:137], v[190:193], v[122:125]
	v_mfma_f32_16x16x32_bf16 v[114:117], v[142:145], v[190:193], v[114:117]
	v_mfma_f32_16x16x32_bf16 v[106:109], v[134:137], v[186:189], v[106:109]
	v_mfma_f32_16x16x32_bf16 v[98:101], v[142:145], v[186:189], v[98:101]
	v_mfma_f32_16x16x32_bf16 v[90:93], v[134:137], v[182:185], v[90:93]
	v_mfma_f32_16x16x32_bf16 v[82:85], v[142:145], v[182:185], v[82:85]
	v_mfma_f32_16x16x32_bf16 v[74:77], v[134:137], v[178:181], v[74:77]
	v_mfma_f32_16x16x32_bf16 v[66:69], v[142:145], v[178:181], v[66:69]
	s_setprio 0
	s_barrier
	v_cndmask_b32_e64 v246, 0, 1, s[50:51]
	v_cmp_ne_u32_e64 s[48:49], 1, v246
	s_andn2_b64 vcc, exec, s[50:51]
	s_cbranch_vccnz .LBB0_178
	ds_read_b128 v[174:177], v244 offset:16384
	ds_read_b128 v[190:193], v244 offset:17408
	ds_read_b128 v[170:173], v244 offset:18432
	ds_read_b128 v[186:189], v244 offset:19456
	ds_read_b128 v[166:169], v244 offset:20480
	ds_read_b128 v[182:185], v244 offset:21504
	ds_read_b128 v[162:165], v244 offset:22528
	ds_read_b128 v[178:181], v244 offset:23552
.LBB0_178:
	s_add_u32 s82, s0, s80
	s_addc_u32 s83, s1, s81
	s_add_u32 s84, s82, 0x460000
	s_addc_u32 s85, s83, 0
	s_cmp_eq_u32 s80, 0x41a0000
	s_cselect_b64 s[86:87], -1, 0
	s_and_b64 s[82:83], s[86:87], exec
	s_cselect_b32 s83, s71, s97
	s_cselect_b32 s82, s73, s79
	s_mov_b32 m0, s9
	s_cselect_b32 s85, s22, s85
	s_cselect_b32 s84, s69, s84
	s_add_u32 vcc_lo, s82, 0x4000
	global_load_lds_dwordx4 v194, s[82:83]
	s_mov_b32 m0, s10
	s_addc_u32 vcc_hi, s83, 0
	global_load_lds_dwordx4 v196, s[82:83]
	s_mov_b32 m0, s11
	s_nop 0
	global_load_lds_dwordx4 v194, vcc
	v_lshl_add_u64 v[246:247], vcc, 0, v[196:197]
	s_mov_b32 m0, s12
	s_and_b64 vcc, exec, s[48:49]
	global_load_lds_dwordx4 v[246:247], off
	s_mov_b64 s[98:99], s[84:85]
	s_waitcnt vmcnt(6)
	s_waitcnt lgkmcnt(0)
	s_barrier
	s_cbranch_vccnz .LBB0_180
	s_setprio 1
	s_waitcnt lgkmcnt(0)
	v_mfma_f32_16x16x32_bf16 v[54:57], v[146:149], v[174:177], v[54:57]
	v_mfma_f32_16x16x32_bf16 v[62:65], v[154:157], v[174:177], v[62:65]
	v_mfma_f32_16x16x32_bf16 v[38:41], v[146:149], v[170:173], v[38:41]
	v_mfma_f32_16x16x32_bf16 v[46:49], v[154:157], v[170:173], v[46:49]
	v_mfma_f32_16x16x32_bf16 v[22:25], v[146:149], v[166:169], v[22:25]
	v_mfma_f32_16x16x32_bf16 v[30:33], v[154:157], v[166:169], v[30:33]
	v_mfma_f32_16x16x32_bf16 v[10:13], v[146:149], v[162:165], v[10:13]
	v_mfma_f32_16x16x32_bf16 v[14:17], v[154:157], v[162:165], v[14:17]
	v_mfma_f32_16x16x32_bf16 v[54:57], v[150:153], v[190:193], v[54:57]
	v_mfma_f32_16x16x32_bf16 v[62:65], v[158:161], v[190:193], v[62:65]
	v_mfma_f32_16x16x32_bf16 v[38:41], v[150:153], v[186:189], v[38:41]
	v_mfma_f32_16x16x32_bf16 v[46:49], v[158:161], v[186:189], v[46:49]
	v_mfma_f32_16x16x32_bf16 v[22:25], v[150:153], v[182:185], v[22:25]
	v_mfma_f32_16x16x32_bf16 v[30:33], v[158:161], v[182:185], v[30:33]
	v_mfma_f32_16x16x32_bf16 v[10:13], v[150:153], v[178:181], v[10:13]
	v_mfma_f32_16x16x32_bf16 v[14:17], v[158:161], v[178:181], v[14:17]
	s_setprio 0
	s_setprio 1
	v_mfma_f32_16x16x32_bf16 v[58:61], v[130:133], v[174:177], v[58:61]
	v_mfma_f32_16x16x32_bf16 v[50:53], v[138:141], v[174:177], v[50:53]
	v_mfma_f32_16x16x32_bf16 v[42:45], v[130:133], v[170:173], v[42:45]
	v_mfma_f32_16x16x32_bf16 v[34:37], v[138:141], v[170:173], v[34:37]
	v_mfma_f32_16x16x32_bf16 v[26:29], v[130:133], v[166:169], v[26:29]
	v_mfma_f32_16x16x32_bf16 v[18:21], v[138:141], v[166:169], v[18:21]
	v_mfma_f32_16x16x32_bf16 v[6:9], v[130:133], v[162:165], v[6:9]
	v_mfma_f32_16x16x32_bf16 v[2:5], v[138:141], v[162:165], v[2:5]
	v_mfma_f32_16x16x32_bf16 v[58:61], v[134:137], v[190:193], v[58:61]
	v_mfma_f32_16x16x32_bf16 v[50:53], v[142:145], v[190:193], v[50:53]
	v_mfma_f32_16x16x32_bf16 v[42:45], v[134:137], v[186:189], v[42:45]
	v_mfma_f32_16x16x32_bf16 v[34:37], v[142:145], v[186:189], v[34:37]
	v_mfma_f32_16x16x32_bf16 v[26:29], v[134:137], v[182:185], v[26:29]
	v_mfma_f32_16x16x32_bf16 v[18:21], v[142:145], v[182:185], v[18:21]
	v_mfma_f32_16x16x32_bf16 v[6:9], v[134:137], v[178:181], v[6:9]
	v_mfma_f32_16x16x32_bf16 v[2:5], v[142:145], v[178:181], v[2:5]
	s_setprio 0
.LBB0_180:
	s_and_b64 vcc, s[46:47], s[86:87]
	v_cndmask_b32_e64 v131, v233, 0, vcc
	v_cndmask_b32_e32 v130, v232, v198, vcc
	v_lshl_add_u64 v[246:247], s[84:85], 0, v[130:131]
	s_barrier
	s_mov_b32 m0, s8
	s_nop 0
	global_load_lds_dwordx4 v194, s[98:99]
	s_mov_b32 m0, s13
	s_nop 0
	global_load_lds_dwordx4 v196, s[98:99]
	v_add_u32_e32 v130, 0x18000, v243
	v_add_u32_e32 v142, 0x1c000, v243
	ds_read_b128 v[146:149], v130
	ds_read_b128 v[150:153], v130 offset:1024
	ds_read_b128 v[154:157], v130 offset:2048
	ds_read_b128 v[158:161], v130 offset:3072
	ds_read_b128 v[130:133], v142
	ds_read_b128 v[134:137], v142 offset:1024
	ds_read_b128 v[138:141], v142 offset:2048
	ds_read_b128 v[142:145], v142 offset:3072
	s_mov_b32 m0, s14
	v_lshl_add_u64 v[248:249], v[246:247], 0, v[194:195]
	s_waitcnt lgkmcnt(0)
	ds_read_b128 v[174:177], v244 offset:32768
	ds_read_b128 v[190:193], v244 offset:33792
	ds_read_b128 v[170:173], v244 offset:34816
	ds_read_b128 v[186:189], v244 offset:35840
	ds_read_b128 v[166:169], v244 offset:36864
	ds_read_b128 v[182:185], v244 offset:37888
	ds_read_b128 v[162:165], v244 offset:38912
	ds_read_b128 v[178:181], v244 offset:39936
	global_load_lds_dwordx4 v[248:249], off
	v_lshl_add_u64 v[246:247], v[246:247], 0, v[196:197]
	s_mov_b32 m0, s15
	s_nop 0
	global_load_lds_dwordx4 v[246:247], off
	s_waitcnt vmcnt(8)
	s_waitcnt lgkmcnt(0)
	s_barrier
	s_setprio 1
	s_waitcnt lgkmcnt(0)
	v_mfma_f32_16x16x32_bf16 v[118:121], v[146:149], v[174:177], v[118:121]
	v_mfma_f32_16x16x32_bf16 v[126:129], v[154:157], v[174:177], v[126:129]
	v_mfma_f32_16x16x32_bf16 v[102:105], v[146:149], v[170:173], v[102:105]
	v_mfma_f32_16x16x32_bf16 v[110:113], v[154:157], v[170:173], v[110:113]
	v_mfma_f32_16x16x32_bf16 v[86:89], v[146:149], v[166:169], v[86:89]
	v_mfma_f32_16x16x32_bf16 v[94:97], v[154:157], v[166:169], v[94:97]
	v_mfma_f32_16x16x32_bf16 v[70:73], v[146:149], v[162:165], v[70:73]
	v_mfma_f32_16x16x32_bf16 v[78:81], v[154:157], v[162:165], v[78:81]
	v_mfma_f32_16x16x32_bf16 v[118:121], v[150:153], v[190:193], v[118:121]
	v_mfma_f32_16x16x32_bf16 v[126:129], v[158:161], v[190:193], v[126:129]
	v_mfma_f32_16x16x32_bf16 v[102:105], v[150:153], v[186:189], v[102:105]
	v_mfma_f32_16x16x32_bf16 v[110:113], v[158:161], v[186:189], v[110:113]
	v_mfma_f32_16x16x32_bf16 v[86:89], v[150:153], v[182:185], v[86:89]
	v_mfma_f32_16x16x32_bf16 v[94:97], v[158:161], v[182:185], v[94:97]
	v_mfma_f32_16x16x32_bf16 v[70:73], v[150:153], v[178:181], v[70:73]
	v_mfma_f32_16x16x32_bf16 v[78:81], v[158:161], v[178:181], v[78:81]
	s_setprio 0
	s_setprio 1
	v_mfma_f32_16x16x32_bf16 v[122:125], v[130:133], v[174:177], v[122:125]
	v_mfma_f32_16x16x32_bf16 v[114:117], v[138:141], v[174:177], v[114:117]
	v_mfma_f32_16x16x32_bf16 v[106:109], v[130:133], v[170:173], v[106:109]
	v_mfma_f32_16x16x32_bf16 v[98:101], v[138:141], v[170:173], v[98:101]
	v_mfma_f32_16x16x32_bf16 v[90:93], v[130:133], v[166:169], v[90:93]
	v_mfma_f32_16x16x32_bf16 v[82:85], v[138:141], v[166:169], v[82:85]
	v_mfma_f32_16x16x32_bf16 v[74:77], v[130:133], v[162:165], v[74:77]
	v_mfma_f32_16x16x32_bf16 v[66:69], v[138:141], v[162:165], v[66:69]
	v_mfma_f32_16x16x32_bf16 v[122:125], v[134:137], v[190:193], v[122:125]
	v_mfma_f32_16x16x32_bf16 v[114:117], v[142:145], v[190:193], v[114:117]
	v_mfma_f32_16x16x32_bf16 v[106:109], v[134:137], v[186:189], v[106:109]
	v_mfma_f32_16x16x32_bf16 v[98:101], v[142:145], v[186:189], v[98:101]
	v_mfma_f32_16x16x32_bf16 v[90:93], v[134:137], v[182:185], v[90:93]
	v_mfma_f32_16x16x32_bf16 v[82:85], v[142:145], v[182:185], v[82:85]
	v_mfma_f32_16x16x32_bf16 v[74:77], v[134:137], v[178:181], v[74:77]
	v_mfma_f32_16x16x32_bf16 v[66:69], v[142:145], v[178:181], v[66:69]
	s_setprio 0
	s_barrier
	s_and_b64 vcc, exec, s[48:49]
	s_cbranch_vccnz .LBB0_182
	ds_read_b128 v[174:177], v244 offset:49152
	ds_read_b128 v[190:193], v244 offset:50176
	ds_read_b128 v[170:173], v244 offset:51200
	ds_read_b128 v[186:189], v244 offset:52224
	ds_read_b128 v[166:169], v244 offset:53248
	ds_read_b128 v[182:185], v244 offset:54272
	ds_read_b128 v[162:165], v244 offset:55296
	ds_read_b128 v[178:181], v244 offset:56320
.LBB0_182:
	s_add_u32 s86, s82, 0x120000
	s_addc_u32 s87, s83, 0
	s_add_u32 s84, s84, 0x230000
	s_addc_u32 s85, s85, 0
	s_mov_b32 m0, s17
	s_add_u32 s82, s82, 0x124000
	global_load_lds_dwordx4 v194, s[86:87]
	s_mov_b32 m0, s54
	s_addc_u32 s83, s83, 0
	global_load_lds_dwordx4 v196, s[86:87]
	s_mov_b32 m0, s89
	s_and_b64 vcc, exec, s[48:49]
	global_load_lds_dwordx4 v194, s[82:83]
	s_mov_b32 m0, s90
	s_nop 0
	global_load_lds_dwordx4 v196, s[82:83]
	s_mov_b64 s[100:101], s[84:85]
	s_waitcnt vmcnt(6)
	s_waitcnt lgkmcnt(0)
	s_barrier
	s_cbranch_vccnz .LBB0_175
	s_setprio 1
	s_waitcnt lgkmcnt(0)
	v_mfma_f32_16x16x32_bf16 v[54:57], v[146:149], v[174:177], v[54:57]
	v_mfma_f32_16x16x32_bf16 v[62:65], v[154:157], v[174:177], v[62:65]
	v_mfma_f32_16x16x32_bf16 v[38:41], v[146:149], v[170:173], v[38:41]
	v_mfma_f32_16x16x32_bf16 v[46:49], v[154:157], v[170:173], v[46:49]
	v_mfma_f32_16x16x32_bf16 v[22:25], v[146:149], v[166:169], v[22:25]
	v_mfma_f32_16x16x32_bf16 v[30:33], v[154:157], v[166:169], v[30:33]
	v_mfma_f32_16x16x32_bf16 v[10:13], v[146:149], v[162:165], v[10:13]
	v_mfma_f32_16x16x32_bf16 v[14:17], v[154:157], v[162:165], v[14:17]
	v_mfma_f32_16x16x32_bf16 v[54:57], v[150:153], v[190:193], v[54:57]
	v_mfma_f32_16x16x32_bf16 v[62:65], v[158:161], v[190:193], v[62:65]
	v_mfma_f32_16x16x32_bf16 v[38:41], v[150:153], v[186:189], v[38:41]
	v_mfma_f32_16x16x32_bf16 v[46:49], v[158:161], v[186:189], v[46:49]
	v_mfma_f32_16x16x32_bf16 v[22:25], v[150:153], v[182:185], v[22:25]
	v_mfma_f32_16x16x32_bf16 v[30:33], v[158:161], v[182:185], v[30:33]
	v_mfma_f32_16x16x32_bf16 v[10:13], v[150:153], v[178:181], v[10:13]
	v_mfma_f32_16x16x32_bf16 v[14:17], v[158:161], v[178:181], v[14:17]
	s_setprio 0
	s_setprio 1
	v_mfma_f32_16x16x32_bf16 v[58:61], v[130:133], v[174:177], v[58:61]
	v_mfma_f32_16x16x32_bf16 v[50:53], v[138:141], v[174:177], v[50:53]
	v_mfma_f32_16x16x32_bf16 v[42:45], v[130:133], v[170:173], v[42:45]
	v_mfma_f32_16x16x32_bf16 v[34:37], v[138:141], v[170:173], v[34:37]
	v_mfma_f32_16x16x32_bf16 v[26:29], v[130:133], v[166:169], v[26:29]
	v_mfma_f32_16x16x32_bf16 v[18:21], v[138:141], v[166:169], v[18:21]
	v_mfma_f32_16x16x32_bf16 v[6:9], v[130:133], v[162:165], v[6:9]
	v_mfma_f32_16x16x32_bf16 v[2:5], v[138:141], v[162:165], v[2:5]
	v_mfma_f32_16x16x32_bf16 v[58:61], v[134:137], v[190:193], v[58:61]
	v_mfma_f32_16x16x32_bf16 v[50:53], v[142:145], v[190:193], v[50:53]
	v_mfma_f32_16x16x32_bf16 v[42:45], v[134:137], v[186:189], v[42:45]
	v_mfma_f32_16x16x32_bf16 v[34:37], v[142:145], v[186:189], v[34:37]
	v_mfma_f32_16x16x32_bf16 v[26:29], v[134:137], v[182:185], v[26:29]
	v_mfma_f32_16x16x32_bf16 v[18:21], v[142:145], v[182:185], v[18:21]
	v_mfma_f32_16x16x32_bf16 v[6:9], v[134:137], v[178:181], v[6:9]
	v_mfma_f32_16x16x32_bf16 v[2:5], v[142:145], v[178:181], v[2:5]
	s_setprio 0
	s_branch .LBB0_175

.LBB0_559:
	s_mov_b32 m0, s55
	s_nop 0
	global_load_lds_dwordx4 v194, s[100:101]
	s_mov_b32 m0, s67
	s_nop 0
	global_load_lds_dwordx4 v196, s[100:101]
	ds_read_b128 v[146:149], v227
	ds_read_b128 v[150:153], v227 offset:1024
	ds_read_b128 v[154:157], v227 offset:2048
	ds_read_b128 v[158:161], v227 offset:3072
	ds_read_b128 v[130:133], v228
	ds_read_b128 v[134:137], v228 offset:1024
	ds_read_b128 v[138:141], v228 offset:2048
	ds_read_b128 v[142:145], v228 offset:3072
	v_lshl_add_u64 v[234:235], v[216:217], 0, s[58:59]
	s_add_i32 m0, s8, 0xc000
	s_waitcnt lgkmcnt(0)
	ds_read_b128 v[174:177], v229
	ds_read_b128 v[190:193], v229 offset:1024
	ds_read_b128 v[170:173], v229 offset:2048
	ds_read_b128 v[186:189], v229 offset:3072
	ds_read_b128 v[166:169], v229 offset:4096
	ds_read_b128 v[182:185], v229 offset:5120
	ds_read_b128 v[162:165], v229 offset:6144
	ds_read_b128 v[178:181], v229 offset:7168
	global_load_lds_dwordx4 v[234:235], off
	v_lshl_add_u64 v[234:235], v[218:219], 0, s[58:59]
	s_add_i32 m0, s8, 0xe000
	s_nop 0
	global_load_lds_dwordx4 v[234:235], off
	s_waitcnt vmcnt(8)
	s_waitcnt lgkmcnt(0)
	s_barrier
	s_setprio 1
	s_waitcnt lgkmcnt(0)
	v_mfma_f32_16x16x32_bf16 v[126:129], v[146:149], v[174:177], v[126:129]
	v_mfma_f32_16x16x32_bf16 v[122:125], v[154:157], v[174:177], v[122:125]
	v_mfma_f32_16x16x32_bf16 v[110:113], v[146:149], v[170:173], v[110:113]
	v_mfma_f32_16x16x32_bf16 v[106:109], v[154:157], v[170:173], v[106:109]
	v_mfma_f32_16x16x32_bf16 v[94:97], v[146:149], v[166:169], v[94:97]
	v_mfma_f32_16x16x32_bf16 v[90:93], v[154:157], v[166:169], v[90:93]
	v_mfma_f32_16x16x32_bf16 v[78:81], v[146:149], v[162:165], v[78:81]
	v_mfma_f32_16x16x32_bf16 v[74:77], v[154:157], v[162:165], v[74:77]
	v_mfma_f32_16x16x32_bf16 v[126:129], v[150:153], v[190:193], v[126:129]
	v_mfma_f32_16x16x32_bf16 v[122:125], v[158:161], v[190:193], v[122:125]
	v_mfma_f32_16x16x32_bf16 v[110:113], v[150:153], v[186:189], v[110:113]
	v_mfma_f32_16x16x32_bf16 v[106:109], v[158:161], v[186:189], v[106:109]
	v_mfma_f32_16x16x32_bf16 v[94:97], v[150:153], v[182:185], v[94:97]
	v_mfma_f32_16x16x32_bf16 v[90:93], v[158:161], v[182:185], v[90:93]
	v_mfma_f32_16x16x32_bf16 v[78:81], v[150:153], v[178:181], v[78:81]
	v_mfma_f32_16x16x32_bf16 v[74:77], v[158:161], v[178:181], v[74:77]
	s_setprio 0
	s_setprio 1
	v_mfma_f32_16x16x32_bf16 v[118:121], v[130:133], v[174:177], v[118:121]
	v_mfma_f32_16x16x32_bf16 v[114:117], v[138:141], v[174:177], v[114:117]
	v_mfma_f32_16x16x32_bf16 v[102:105], v[130:133], v[170:173], v[102:105]
	v_mfma_f32_16x16x32_bf16 v[98:101], v[138:141], v[170:173], v[98:101]
	v_mfma_f32_16x16x32_bf16 v[86:89], v[130:133], v[166:169], v[86:89]
	v_mfma_f32_16x16x32_bf16 v[82:85], v[138:141], v[166:169], v[82:85]
	v_mfma_f32_16x16x32_bf16 v[70:73], v[130:133], v[162:165], v[70:73]
	v_mfma_f32_16x16x32_bf16 v[66:69], v[138:141], v[162:165], v[66:69]
	v_mfma_f32_16x16x32_bf16 v[118:121], v[134:137], v[190:193], v[118:121]
	v_mfma_f32_16x16x32_bf16 v[114:117], v[142:145], v[190:193], v[114:117]
	v_mfma_f32_16x16x32_bf16 v[102:105], v[134:137], v[186:189], v[102:105]
	v_mfma_f32_16x16x32_bf16 v[98:101], v[142:145], v[186:189], v[98:101]
	v_mfma_f32_16x16x32_bf16 v[86:89], v[134:137], v[182:185], v[86:89]
	v_mfma_f32_16x16x32_bf16 v[82:85], v[142:145], v[182:185], v[82:85]
	v_mfma_f32_16x16x32_bf16 v[70:73], v[134:137], v[178:181], v[70:73]
	v_mfma_f32_16x16x32_bf16 v[66:69], v[142:145], v[178:181], v[66:69]
	s_setprio 0
	s_barrier
	v_cmp_ne_u32_e64 s[42:43], 1, v233
	s_andn2_b64 vcc, exec, s[44:45]
	s_cbranch_vccnz .LBB0_561
	ds_read_b128 v[174:177], v229 offset:16384
	ds_read_b128 v[190:193], v229 offset:17408
	ds_read_b128 v[170:173], v229 offset:18432
	ds_read_b128 v[186:189], v229 offset:19456
	ds_read_b128 v[166:169], v229 offset:20480
	ds_read_b128 v[182:185], v229 offset:21504
	ds_read_b128 v[162:165], v229 offset:22528
	ds_read_b128 v[178:181], v229 offset:23552
.LBB0_561:
	s_add_u32 s60, s56, s58
	s_addc_u32 s61, s57, s59
	s_add_u32 s62, s60, 0x440000
	s_addc_u32 s63, s61, 0
	s_cmp_eq_u32 s58, 0x3fc0000
	s_cselect_b64 s[68:69], -1, 0
	s_and_b64 s[60:61], s[68:69], exec
	s_cselect_b32 s61, s37, s72
	s_cselect_b32 s60, s47, s53
	s_mov_b32 m0, s9
	s_cselect_b32 s63, s1, s63
	s_cselect_b32 s62, s24, s62
	s_add_u32 s74, s60, 0x4000
	global_load_lds_dwordx4 v194, s[60:61]
	s_mov_b32 m0, s10
	s_addc_u32 s75, s61, 0
	global_load_lds_dwordx4 v196, s[60:61]
	s_mov_b32 m0, s11
	s_and_b64 vcc, exec, s[42:43]
	global_load_lds_dwordx4 v194, s[74:75]
	s_mov_b32 m0, s12
	s_nop 0
	global_load_lds_dwordx4 v196, s[74:75]
	s_mov_b64 s[98:99], s[62:63]
	s_waitcnt vmcnt(6)
	s_waitcnt lgkmcnt(0)
	s_barrier
	s_cbranch_vccnz .LBB0_563
	s_setprio 1
	s_waitcnt lgkmcnt(0)
	v_mfma_f32_16x16x32_bf16 v[62:65], v[146:149], v[174:177], v[62:65]
	v_mfma_f32_16x16x32_bf16 v[58:61], v[154:157], v[174:177], v[58:61]
	v_mfma_f32_16x16x32_bf16 v[46:49], v[146:149], v[170:173], v[46:49]
	v_mfma_f32_16x16x32_bf16 v[42:45], v[154:157], v[170:173], v[42:45]
	v_mfma_f32_16x16x32_bf16 v[30:33], v[146:149], v[166:169], v[30:33]
	v_mfma_f32_16x16x32_bf16 v[26:29], v[154:157], v[166:169], v[26:29]
	v_mfma_f32_16x16x32_bf16 v[14:17], v[146:149], v[162:165], v[14:17]
	v_mfma_f32_16x16x32_bf16 v[10:13], v[154:157], v[162:165], v[10:13]
	v_mfma_f32_16x16x32_bf16 v[62:65], v[150:153], v[190:193], v[62:65]
	v_mfma_f32_16x16x32_bf16 v[58:61], v[158:161], v[190:193], v[58:61]
	v_mfma_f32_16x16x32_bf16 v[46:49], v[150:153], v[186:189], v[46:49]
	v_mfma_f32_16x16x32_bf16 v[42:45], v[158:161], v[186:189], v[42:45]
	v_mfma_f32_16x16x32_bf16 v[30:33], v[150:153], v[182:185], v[30:33]
	v_mfma_f32_16x16x32_bf16 v[26:29], v[158:161], v[182:185], v[26:29]
	v_mfma_f32_16x16x32_bf16 v[14:17], v[150:153], v[178:181], v[14:17]
	v_mfma_f32_16x16x32_bf16 v[10:13], v[158:161], v[178:181], v[10:13]
	s_setprio 0
	s_setprio 1
	v_mfma_f32_16x16x32_bf16 v[54:57], v[130:133], v[174:177], v[54:57]
	v_mfma_f32_16x16x32_bf16 v[50:53], v[138:141], v[174:177], v[50:53]
	v_mfma_f32_16x16x32_bf16 v[38:41], v[130:133], v[170:173], v[38:41]
	v_mfma_f32_16x16x32_bf16 v[34:37], v[138:141], v[170:173], v[34:37]
	v_mfma_f32_16x16x32_bf16 v[22:25], v[130:133], v[166:169], v[22:25]
	v_mfma_f32_16x16x32_bf16 v[18:21], v[138:141], v[166:169], v[18:21]
	v_mfma_f32_16x16x32_bf16 v[6:9], v[130:133], v[162:165], v[6:9]
	v_mfma_f32_16x16x32_bf16 v[2:5], v[138:141], v[162:165], v[2:5]
	v_mfma_f32_16x16x32_bf16 v[54:57], v[134:137], v[190:193], v[54:57]
	v_mfma_f32_16x16x32_bf16 v[50:53], v[142:145], v[190:193], v[50:53]
	v_mfma_f32_16x16x32_bf16 v[38:41], v[134:137], v[186:189], v[38:41]
	v_mfma_f32_16x16x32_bf16 v[34:37], v[142:145], v[186:189], v[34:37]
	v_mfma_f32_16x16x32_bf16 v[22:25], v[134:137], v[182:185], v[22:25]
	v_mfma_f32_16x16x32_bf16 v[18:21], v[142:145], v[182:185], v[18:21]
	v_mfma_f32_16x16x32_bf16 v[6:9], v[134:137], v[178:181], v[6:9]
	v_mfma_f32_16x16x32_bf16 v[2:5], v[142:145], v[178:181], v[2:5]
	s_setprio 0
.LBB0_563:
	s_and_b64 vcc, s[40:41], s[68:69]
	v_cndmask_b32_e64 v131, v215, 0, vcc
	v_cndmask_b32_e32 v130, v214, v198, vcc
	v_lshl_add_u64 v[234:235], s[62:63], 0, v[130:131]
	s_barrier
	s_mov_b32 m0, s8
	s_nop 0
	global_load_lds_dwordx4 v194, s[98:99]
	s_mov_b32 m0, s13
	s_nop 0
	global_load_lds_dwordx4 v196, s[98:99]
	v_add_u32_e32 v130, 0x18000, v226
	v_add_u32_e32 v142, 0x1c000, v226
	ds_read_b128 v[146:149], v130
	ds_read_b128 v[150:153], v130 offset:1024
	ds_read_b128 v[154:157], v130 offset:2048
	ds_read_b128 v[158:161], v130 offset:3072
	ds_read_b128 v[130:133], v142
	ds_read_b128 v[134:137], v142 offset:1024
	ds_read_b128 v[138:141], v142 offset:2048
	ds_read_b128 v[142:145], v142 offset:3072
	s_mov_b32 m0, s14
	v_lshl_add_u64 v[236:237], v[234:235], 0, v[194:195]
	s_waitcnt lgkmcnt(0)
	ds_read_b128 v[174:177], v229 offset:32768
	ds_read_b128 v[190:193], v229 offset:33792
	ds_read_b128 v[170:173], v229 offset:34816
	ds_read_b128 v[186:189], v229 offset:35840
	ds_read_b128 v[166:169], v229 offset:36864
	ds_read_b128 v[182:185], v229 offset:37888
	ds_read_b128 v[162:165], v229 offset:38912
	ds_read_b128 v[178:181], v229 offset:39936
	global_load_lds_dwordx4 v[236:237], off
	v_lshl_add_u64 v[234:235], v[234:235], 0, v[196:197]
	s_mov_b32 m0, s15
	s_nop 0
	global_load_lds_dwordx4 v[234:235], off
	s_waitcnt vmcnt(8)
	s_waitcnt lgkmcnt(0)
	s_barrier
	s_setprio 1
	s_waitcnt lgkmcnt(0)
	v_mfma_f32_16x16x32_bf16 v[126:129], v[146:149], v[174:177], v[126:129]
	v_mfma_f32_16x16x32_bf16 v[122:125], v[154:157], v[174:177], v[122:125]
	v_mfma_f32_16x16x32_bf16 v[110:113], v[146:149], v[170:173], v[110:113]
	v_mfma_f32_16x16x32_bf16 v[106:109], v[154:157], v[170:173], v[106:109]
	v_mfma_f32_16x16x32_bf16 v[94:97], v[146:149], v[166:169], v[94:97]
	v_mfma_f32_16x16x32_bf16 v[90:93], v[154:157], v[166:169], v[90:93]
	v_mfma_f32_16x16x32_bf16 v[78:81], v[146:149], v[162:165], v[78:81]
	v_mfma_f32_16x16x32_bf16 v[74:77], v[154:157], v[162:165], v[74:77]
	v_mfma_f32_16x16x32_bf16 v[126:129], v[150:153], v[190:193], v[126:129]
	v_mfma_f32_16x16x32_bf16 v[122:125], v[158:161], v[190:193], v[122:125]
	v_mfma_f32_16x16x32_bf16 v[110:113], v[150:153], v[186:189], v[110:113]
	v_mfma_f32_16x16x32_bf16 v[106:109], v[158:161], v[186:189], v[106:109]
	v_mfma_f32_16x16x32_bf16 v[94:97], v[150:153], v[182:185], v[94:97]
	v_mfma_f32_16x16x32_bf16 v[90:93], v[158:161], v[182:185], v[90:93]
	v_mfma_f32_16x16x32_bf16 v[78:81], v[150:153], v[178:181], v[78:81]
	v_mfma_f32_16x16x32_bf16 v[74:77], v[158:161], v[178:181], v[74:77]
	s_setprio 0
	s_setprio 1
	v_mfma_f32_16x16x32_bf16 v[118:121], v[130:133], v[174:177], v[118:121]
	v_mfma_f32_16x16x32_bf16 v[114:117], v[138:141], v[174:177], v[114:117]
	v_mfma_f32_16x16x32_bf16 v[102:105], v[130:133], v[170:173], v[102:105]
	v_mfma_f32_16x16x32_bf16 v[98:101], v[138:141], v[170:173], v[98:101]
	v_mfma_f32_16x16x32_bf16 v[86:89], v[130:133], v[166:169], v[86:89]
	v_mfma_f32_16x16x32_bf16 v[82:85], v[138:141], v[166:169], v[82:85]
	v_mfma_f32_16x16x32_bf16 v[70:73], v[130:133], v[162:165], v[70:73]
	v_mfma_f32_16x16x32_bf16 v[66:69], v[138:141], v[162:165], v[66:69]
	v_mfma_f32_16x16x32_bf16 v[118:121], v[134:137], v[190:193], v[118:121]
	v_mfma_f32_16x16x32_bf16 v[114:117], v[142:145], v[190:193], v[114:117]
	v_mfma_f32_16x16x32_bf16 v[102:105], v[134:137], v[186:189], v[102:105]
	v_mfma_f32_16x16x32_bf16 v[98:101], v[142:145], v[186:189], v[98:101]
	v_mfma_f32_16x16x32_bf16 v[86:89], v[134:137], v[182:185], v[86:89]
	v_mfma_f32_16x16x32_bf16 v[82:85], v[142:145], v[182:185], v[82:85]
	v_mfma_f32_16x16x32_bf16 v[70:73], v[134:137], v[178:181], v[70:73]
	v_mfma_f32_16x16x32_bf16 v[66:69], v[142:145], v[178:181], v[66:69]
	s_setprio 0
	s_barrier
	s_and_b64 vcc, exec, s[42:43]
	s_cbranch_vccnz .LBB0_565
	ds_read_b128 v[174:177], v229 offset:49152
	ds_read_b128 v[190:193], v229 offset:50176
	ds_read_b128 v[170:173], v229 offset:51200
	ds_read_b128 v[186:189], v229 offset:52224
	ds_read_b128 v[166:169], v229 offset:53248
	ds_read_b128 v[182:185], v229 offset:54272
	ds_read_b128 v[162:165], v229 offset:55296
	ds_read_b128 v[178:181], v229 offset:56320
.LBB0_565:
	s_add_u32 s68, s60, 0x40000
	s_addc_u32 s69, s61, 0
	s_add_u32 s62, s62, 0x220000
	s_addc_u32 s63, s63, 0
	s_mov_b32 m0, s17
	s_add_u32 s60, s60, 0x44000
	global_load_lds_dwordx4 v194, s[68:69]
	s_mov_b32 m0, s54
	s_addc_u32 s61, s61, 0
	global_load_lds_dwordx4 v196, s[68:69]
	s_mov_b32 m0, s70
	s_and_b64 vcc, exec, s[42:43]
	global_load_lds_dwordx4 v194, s[60:61]
	s_mov_b32 m0, s71
	s_nop 0
	global_load_lds_dwordx4 v196, s[60:61]
	s_mov_b64 s[100:101], s[62:63]
	s_waitcnt vmcnt(6)
	s_waitcnt lgkmcnt(0)
	s_barrier
	s_cbranch_vccnz .LBB0_558
	s_setprio 1
	s_waitcnt lgkmcnt(0)
	v_mfma_f32_16x16x32_bf16 v[62:65], v[146:149], v[174:177], v[62:65]
	v_mfma_f32_16x16x32_bf16 v[58:61], v[154:157], v[174:177], v[58:61]
	v_mfma_f32_16x16x32_bf16 v[46:49], v[146:149], v[170:173], v[46:49]
	v_mfma_f32_16x16x32_bf16 v[42:45], v[154:157], v[170:173], v[42:45]
	v_mfma_f32_16x16x32_bf16 v[30:33], v[146:149], v[166:169], v[30:33]
	v_mfma_f32_16x16x32_bf16 v[26:29], v[154:157], v[166:169], v[26:29]
	v_mfma_f32_16x16x32_bf16 v[14:17], v[146:149], v[162:165], v[14:17]
	v_mfma_f32_16x16x32_bf16 v[10:13], v[154:157], v[162:165], v[10:13]
	v_mfma_f32_16x16x32_bf16 v[62:65], v[150:153], v[190:193], v[62:65]
	v_mfma_f32_16x16x32_bf16 v[58:61], v[158:161], v[190:193], v[58:61]
	v_mfma_f32_16x16x32_bf16 v[46:49], v[150:153], v[186:189], v[46:49]
	v_mfma_f32_16x16x32_bf16 v[42:45], v[158:161], v[186:189], v[42:45]
	v_mfma_f32_16x16x32_bf16 v[30:33], v[150:153], v[182:185], v[30:33]
	v_mfma_f32_16x16x32_bf16 v[26:29], v[158:161], v[182:185], v[26:29]
	v_mfma_f32_16x16x32_bf16 v[14:17], v[150:153], v[178:181], v[14:17]
	v_mfma_f32_16x16x32_bf16 v[10:13], v[158:161], v[178:181], v[10:13]
	s_setprio 0
	s_setprio 1
	v_mfma_f32_16x16x32_bf16 v[54:57], v[130:133], v[174:177], v[54:57]
	v_mfma_f32_16x16x32_bf16 v[50:53], v[138:141], v[174:177], v[50:53]
	v_mfma_f32_16x16x32_bf16 v[38:41], v[130:133], v[170:173], v[38:41]
	v_mfma_f32_16x16x32_bf16 v[34:37], v[138:141], v[170:173], v[34:37]
	v_mfma_f32_16x16x32_bf16 v[22:25], v[130:133], v[166:169], v[22:25]
	v_mfma_f32_16x16x32_bf16 v[18:21], v[138:141], v[166:169], v[18:21]
	v_mfma_f32_16x16x32_bf16 v[6:9], v[130:133], v[162:165], v[6:9]
	v_mfma_f32_16x16x32_bf16 v[2:5], v[138:141], v[162:165], v[2:5]
	v_mfma_f32_16x16x32_bf16 v[54:57], v[134:137], v[190:193], v[54:57]
	v_mfma_f32_16x16x32_bf16 v[50:53], v[142:145], v[190:193], v[50:53]
	v_mfma_f32_16x16x32_bf16 v[38:41], v[134:137], v[186:189], v[38:41]
	v_mfma_f32_16x16x32_bf16 v[34:37], v[142:145], v[186:189], v[34:37]
	v_mfma_f32_16x16x32_bf16 v[22:25], v[134:137], v[182:185], v[22:25]
	v_mfma_f32_16x16x32_bf16 v[18:21], v[142:145], v[182:185], v[18:21]
	v_mfma_f32_16x16x32_bf16 v[6:9], v[134:137], v[178:181], v[6:9]
	v_mfma_f32_16x16x32_bf16 v[2:5], v[142:145], v[178:181], v[2:5]
	s_setprio 0
	s_branch .LBB0_558

.LBB0_761:
	s_mov_b32 m0, s14
	s_nop 0
	global_load_lds_dwordx4 v194, s[100:101]
	s_mov_b32 m0, s15
	s_nop 0
	global_load_lds_dwordx4 v196, s[100:101]
	ds_read_b128 v[130:133], v237
	ds_read_b128 v[134:137], v237 offset:1024
	ds_read_b128 v[138:141], v237 offset:2048
	ds_read_b128 v[142:145], v237 offset:3072
	ds_read_b128 v[146:149], v238
	ds_read_b128 v[150:153], v238 offset:1024
	ds_read_b128 v[154:157], v238 offset:2048
	ds_read_b128 v[158:161], v238 offset:3072
	s_add_u32 s48, s0, 0x21c000
	s_addc_u32 s49, s1, 0
	s_cmp_eq_u32 s67, 28
	s_cselect_b32 s42, s55, s62
	s_cselect_b32 s43, s29, s63
	s_cselect_b32 s52, s45, s48
	s_cselect_b32 s53, s31, s49
	s_add_u32 s50, s42, 0xe0000
	s_addc_u32 s51, s43, 0
	s_add_u32 s48, s52, 0x220000
	s_addc_u32 s49, s53, 0
	v_lshl_add_u64 v[208:209], s[0:1], 0, v[202:203]
	s_add_i32 m0, s9, 0xc000
	ds_read_b128 v[162:165], v239
	ds_read_b128 v[166:169], v239 offset:1024
	ds_read_b128 v[170:173], v239 offset:2048
	ds_read_b128 v[174:177], v239 offset:3072
	ds_read_b128 v[178:181], v239 offset:4096
	ds_read_b128 v[182:185], v239 offset:5120
	ds_read_b128 v[186:189], v239 offset:6144
	ds_read_b128 v[190:193], v239 offset:7168
	global_load_lds_dwordx4 v[208:209], off
	v_lshl_add_u64 v[208:209], s[0:1], 0, v[200:201]
	s_add_i32 m0, s9, 0xe000
	s_nop 0
	global_load_lds_dwordx4 v[208:209], off
	s_waitcnt vmcnt(8)
	s_waitcnt lgkmcnt(0)
	s_barrier
	s_setprio 1
	s_waitcnt lgkmcnt(0)
	v_mfma_f32_16x16x32_bf16 v[126:129], v[130:133], v[162:165], v[126:129]
	v_mfma_f32_16x16x32_bf16 v[122:125], v[138:141], v[162:165], v[122:125]
	v_mfma_f32_16x16x32_bf16 v[118:121], v[130:133], v[170:173], v[118:121]
	v_mfma_f32_16x16x32_bf16 v[114:117], v[138:141], v[170:173], v[114:117]
	v_mfma_f32_16x16x32_bf16 v[110:113], v[130:133], v[178:181], v[110:113]
	v_mfma_f32_16x16x32_bf16 v[106:109], v[138:141], v[178:181], v[106:109]
	v_mfma_f32_16x16x32_bf16 v[102:105], v[130:133], v[186:189], v[102:105]
	v_mfma_f32_16x16x32_bf16 v[98:101], v[138:141], v[186:189], v[98:101]
	v_mfma_f32_16x16x32_bf16 v[126:129], v[134:137], v[166:169], v[126:129]
	v_mfma_f32_16x16x32_bf16 v[122:125], v[142:145], v[166:169], v[122:125]
	v_mfma_f32_16x16x32_bf16 v[118:121], v[134:137], v[174:177], v[118:121]
	v_mfma_f32_16x16x32_bf16 v[114:117], v[142:145], v[174:177], v[114:117]
	v_mfma_f32_16x16x32_bf16 v[110:113], v[134:137], v[182:185], v[110:113]
	v_mfma_f32_16x16x32_bf16 v[106:109], v[142:145], v[182:185], v[106:109]
	v_mfma_f32_16x16x32_bf16 v[102:105], v[134:137], v[190:193], v[102:105]
	v_mfma_f32_16x16x32_bf16 v[98:101], v[142:145], v[190:193], v[98:101]
	s_setprio 0
	s_setprio 1
	v_mfma_f32_16x16x32_bf16 v[62:65], v[146:149], v[162:165], v[62:65]
	s_add_u32 s60, s52, 0x4000
	s_addc_u32 s61, s53, 0
	v_mfma_f32_16x16x32_bf16 v[58:61], v[154:157], v[162:165], v[58:61]
	v_mfma_f32_16x16x32_bf16 v[54:57], v[146:149], v[170:173], v[54:57]
	v_mfma_f32_16x16x32_bf16 v[50:53], v[154:157], v[170:173], v[50:53]
	v_mfma_f32_16x16x32_bf16 v[46:49], v[146:149], v[178:181], v[46:49]
	v_mfma_f32_16x16x32_bf16 v[42:45], v[154:157], v[178:181], v[42:45]
	v_mfma_f32_16x16x32_bf16 v[38:41], v[146:149], v[186:189], v[38:41]
	v_mfma_f32_16x16x32_bf16 v[34:37], v[154:157], v[186:189], v[34:37]
	v_mfma_f32_16x16x32_bf16 v[62:65], v[150:153], v[166:169], v[62:65]
	v_mfma_f32_16x16x32_bf16 v[58:61], v[158:161], v[166:169], v[58:61]
	v_mfma_f32_16x16x32_bf16 v[54:57], v[150:153], v[174:177], v[54:57]
	v_mfma_f32_16x16x32_bf16 v[50:53], v[158:161], v[174:177], v[50:53]
	v_mfma_f32_16x16x32_bf16 v[46:49], v[150:153], v[182:185], v[46:49]
	v_mfma_f32_16x16x32_bf16 v[42:45], v[158:161], v[182:185], v[42:45]
	v_mfma_f32_16x16x32_bf16 v[38:41], v[150:153], v[190:193], v[38:41]
	v_mfma_f32_16x16x32_bf16 v[34:37], v[158:161], v[190:193], v[34:37]
	s_setprio 0
	s_barrier
	s_add_i32 s68, s16, s8
	s_mov_b32 m0, s68
	ds_read_b128 v[162:165], v239 offset:16384
	ds_read_b128 v[166:169], v239 offset:17408
	ds_read_b128 v[170:173], v239 offset:18432
	ds_read_b128 v[174:177], v239 offset:19456
	ds_read_b128 v[178:181], v239 offset:20480
	ds_read_b128 v[182:185], v239 offset:21504
	ds_read_b128 v[186:189], v239 offset:22528
	ds_read_b128 v[190:193], v239 offset:23552
	global_load_lds_dwordx4 v194, s[42:43]
	s_add_i32 m0, s68, 0x2000
	s_add_u32 s68, s42, 0x4000
	s_addc_u32 s69, s43, 0
	s_add_i32 s70, s17, s8
	global_load_lds_dwordx4 v196, s[42:43]
	s_mov_b32 m0, s70
	s_nop 0
	global_load_lds_dwordx4 v194, s[68:69]
	s_add_i32 m0, s70, 0x2000
	s_nop 0
	global_load_lds_dwordx4 v196, s[68:69]
	s_mov_b64 s[98:99], s[52:53]
	s_waitcnt vmcnt(6)
	s_waitcnt lgkmcnt(0)
	s_barrier
	s_setprio 1
	s_waitcnt lgkmcnt(0)
	v_mfma_f32_16x16x32_bf16 v[94:97], v[130:133], v[162:165], v[94:97]
	v_mfma_f32_16x16x32_bf16 v[90:93], v[138:141], v[162:165], v[90:93]
	v_mfma_f32_16x16x32_bf16 v[86:89], v[130:133], v[170:173], v[86:89]
	v_mfma_f32_16x16x32_bf16 v[82:85], v[138:141], v[170:173], v[82:85]
	v_mfma_f32_16x16x32_bf16 v[78:81], v[130:133], v[178:181], v[78:81]
	v_mfma_f32_16x16x32_bf16 v[74:77], v[138:141], v[178:181], v[74:77]
	v_mfma_f32_16x16x32_bf16 v[70:73], v[130:133], v[186:189], v[70:73]
	v_mfma_f32_16x16x32_bf16 v[66:69], v[138:141], v[186:189], v[66:69]
	v_mfma_f32_16x16x32_bf16 v[94:97], v[134:137], v[166:169], v[94:97]
	v_mfma_f32_16x16x32_bf16 v[90:93], v[142:145], v[166:169], v[90:93]
	v_mfma_f32_16x16x32_bf16 v[86:89], v[134:137], v[174:177], v[86:89]
	v_mfma_f32_16x16x32_bf16 v[82:85], v[142:145], v[174:177], v[82:85]
	v_mfma_f32_16x16x32_bf16 v[78:81], v[134:137], v[182:185], v[78:81]
	v_mfma_f32_16x16x32_bf16 v[74:77], v[142:145], v[182:185], v[74:77]
	v_mfma_f32_16x16x32_bf16 v[70:73], v[134:137], v[190:193], v[70:73]
	v_mfma_f32_16x16x32_bf16 v[66:69], v[142:145], v[190:193], v[66:69]
	s_setprio 0
	s_setprio 1
	v_mfma_f32_16x16x32_bf16 v[30:33], v[146:149], v[162:165], v[30:33]
	v_mfma_f32_16x16x32_bf16 v[26:29], v[154:157], v[162:165], v[26:29]
	v_mfma_f32_16x16x32_bf16 v[22:25], v[146:149], v[170:173], v[22:25]
	v_mfma_f32_16x16x32_bf16 v[18:21], v[154:157], v[170:173], v[18:21]
	v_mfma_f32_16x16x32_bf16 v[14:17], v[146:149], v[178:181], v[14:17]
	v_mfma_f32_16x16x32_bf16 v[10:13], v[154:157], v[178:181], v[10:13]
	v_mfma_f32_16x16x32_bf16 v[6:9], v[146:149], v[186:189], v[6:9]
	v_mfma_f32_16x16x32_bf16 v[2:5], v[154:157], v[186:189], v[2:5]
	v_mfma_f32_16x16x32_bf16 v[30:33], v[150:153], v[166:169], v[30:33]
	v_mfma_f32_16x16x32_bf16 v[26:29], v[158:161], v[166:169], v[26:29]
	v_mfma_f32_16x16x32_bf16 v[22:25], v[150:153], v[174:177], v[22:25]
	v_mfma_f32_16x16x32_bf16 v[18:21], v[158:161], v[174:177], v[18:21]
	v_mfma_f32_16x16x32_bf16 v[14:17], v[150:153], v[182:185], v[14:17]
	v_mfma_f32_16x16x32_bf16 v[10:13], v[158:161], v[182:185], v[10:13]
	v_mfma_f32_16x16x32_bf16 v[6:9], v[150:153], v[190:193], v[6:9]
	v_mfma_f32_16x16x32_bf16 v[2:5], v[158:161], v[190:193], v[2:5]
	s_setprio 0
	s_barrier
	s_mov_b32 m0, s9
	s_nop 0
	global_load_lds_dwordx4 v194, s[98:99]
	s_mov_b32 m0, s10
	s_nop 0
	global_load_lds_dwordx4 v196, s[98:99]
	s_add_i32 s52, 0, 0x18000
	s_add_i32 s53, 0, 0x1c000
	v_add_u32_e32 v142, s52, v228
	v_add_u32_e32 v158, s53, v228
	ds_read_b128 v[130:133], v142
	ds_read_b128 v[134:137], v142 offset:1024
	ds_read_b128 v[138:141], v142 offset:2048
	ds_read_b128 v[142:145], v142 offset:3072
	ds_read_b128 v[146:149], v158
	ds_read_b128 v[150:153], v158 offset:1024
	ds_read_b128 v[154:157], v158 offset:2048
	ds_read_b128 v[158:161], v158 offset:3072
	s_mov_b32 m0, s11
	ds_read_b128 v[162:165], v239 offset:32768
	ds_read_b128 v[166:169], v239 offset:33792
	ds_read_b128 v[170:173], v239 offset:34816
	ds_read_b128 v[174:177], v239 offset:35840
	ds_read_b128 v[178:181], v239 offset:36864
	ds_read_b128 v[182:185], v239 offset:37888
	ds_read_b128 v[186:189], v239 offset:38912
	ds_read_b128 v[190:193], v239 offset:39936
	global_load_lds_dwordx4 v194, s[60:61]
	s_mov_b32 m0, s12
	s_nop 0
	global_load_lds_dwordx4 v196, s[60:61]
	s_waitcnt vmcnt(8)
	s_waitcnt lgkmcnt(0)
	s_barrier
	s_setprio 1
	s_waitcnt lgkmcnt(0)
	v_mfma_f32_16x16x32_bf16 v[126:129], v[130:133], v[162:165], v[126:129]
	v_mfma_f32_16x16x32_bf16 v[122:125], v[138:141], v[162:165], v[122:125]
	v_mfma_f32_16x16x32_bf16 v[118:121], v[130:133], v[170:173], v[118:121]
	v_mfma_f32_16x16x32_bf16 v[114:117], v[138:141], v[170:173], v[114:117]
	v_mfma_f32_16x16x32_bf16 v[110:113], v[130:133], v[178:181], v[110:113]
	v_mfma_f32_16x16x32_bf16 v[106:109], v[138:141], v[178:181], v[106:109]
	v_mfma_f32_16x16x32_bf16 v[102:105], v[130:133], v[186:189], v[102:105]
	v_mfma_f32_16x16x32_bf16 v[98:101], v[138:141], v[186:189], v[98:101]
	v_mfma_f32_16x16x32_bf16 v[126:129], v[134:137], v[166:169], v[126:129]
	v_mfma_f32_16x16x32_bf16 v[122:125], v[142:145], v[166:169], v[122:125]
	v_mfma_f32_16x16x32_bf16 v[118:121], v[134:137], v[174:177], v[118:121]
	v_mfma_f32_16x16x32_bf16 v[114:117], v[142:145], v[174:177], v[114:117]
	v_mfma_f32_16x16x32_bf16 v[110:113], v[134:137], v[182:185], v[110:113]
	v_mfma_f32_16x16x32_bf16 v[106:109], v[142:145], v[182:185], v[106:109]
	v_mfma_f32_16x16x32_bf16 v[102:105], v[134:137], v[190:193], v[102:105]
	v_mfma_f32_16x16x32_bf16 v[98:101], v[142:145], v[190:193], v[98:101]
	s_setprio 0
	s_setprio 1
	v_mfma_f32_16x16x32_bf16 v[62:65], v[146:149], v[162:165], v[62:65]
	v_mfma_f32_16x16x32_bf16 v[58:61], v[154:157], v[162:165], v[58:61]
	v_mfma_f32_16x16x32_bf16 v[54:57], v[146:149], v[170:173], v[54:57]
	v_mfma_f32_16x16x32_bf16 v[50:53], v[154:157], v[170:173], v[50:53]
	v_mfma_f32_16x16x32_bf16 v[46:49], v[146:149], v[178:181], v[46:49]
	v_mfma_f32_16x16x32_bf16 v[42:45], v[154:157], v[178:181], v[42:45]
	v_mfma_f32_16x16x32_bf16 v[38:41], v[146:149], v[186:189], v[38:41]
	v_mfma_f32_16x16x32_bf16 v[34:37], v[154:157], v[186:189], v[34:37]
	v_mfma_f32_16x16x32_bf16 v[62:65], v[150:153], v[166:169], v[62:65]
	v_mfma_f32_16x16x32_bf16 v[58:61], v[158:161], v[166:169], v[58:61]
	v_mfma_f32_16x16x32_bf16 v[54:57], v[150:153], v[174:177], v[54:57]
	v_mfma_f32_16x16x32_bf16 v[50:53], v[158:161], v[174:177], v[50:53]
	v_mfma_f32_16x16x32_bf16 v[46:49], v[150:153], v[182:185], v[46:49]
	v_mfma_f32_16x16x32_bf16 v[42:45], v[158:161], v[182:185], v[42:45]
	v_mfma_f32_16x16x32_bf16 v[38:41], v[150:153], v[190:193], v[38:41]
	v_mfma_f32_16x16x32_bf16 v[34:37], v[158:161], v[190:193], v[34:37]
	s_setprio 0
	s_barrier
	s_add_i32 s52, s52, s8
	s_mov_b32 m0, s52
	ds_read_b128 v[162:165], v239 offset:49152
	ds_read_b128 v[166:169], v239 offset:50176
	ds_read_b128 v[170:173], v239 offset:51200
	ds_read_b128 v[174:177], v239 offset:52224
	ds_read_b128 v[178:181], v239 offset:53248
	ds_read_b128 v[182:185], v239 offset:54272
	ds_read_b128 v[186:189], v239 offset:55296
	ds_read_b128 v[190:193], v239 offset:56320
	global_load_lds_dwordx4 v194, s[50:51]
	s_add_i32 m0, s52, 0x2000
	s_add_u32 s42, s42, 0xe4000
	v_lshl_add_u64 v[208:209], s[50:51], 0, v[196:197]
	s_addc_u32 s43, s43, 0
	s_add_i32 s50, s53, s8
	global_load_lds_dwordx4 v[208:209], off
	s_mov_b32 m0, s50
	s_nop 0
	global_load_lds_dwordx4 v194, s[42:43]
	s_add_i32 m0, s50, 0x2000
	s_nop 0
	global_load_lds_dwordx4 v196, s[42:43]
	s_mov_b64 s[100:101], s[48:49]
	s_waitcnt vmcnt(6)
	s_waitcnt lgkmcnt(0)
	s_barrier
	s_setprio 1
	s_waitcnt lgkmcnt(0)
	v_mfma_f32_16x16x32_bf16 v[94:97], v[130:133], v[162:165], v[94:97]
	v_mfma_f32_16x16x32_bf16 v[90:93], v[138:141], v[162:165], v[90:93]
	v_mfma_f32_16x16x32_bf16 v[86:89], v[130:133], v[170:173], v[86:89]
	v_mfma_f32_16x16x32_bf16 v[82:85], v[138:141], v[170:173], v[82:85]
	v_mfma_f32_16x16x32_bf16 v[78:81], v[130:133], v[178:181], v[78:81]
	v_mfma_f32_16x16x32_bf16 v[74:77], v[138:141], v[178:181], v[74:77]
	v_mfma_f32_16x16x32_bf16 v[70:73], v[130:133], v[186:189], v[70:73]
	v_mfma_f32_16x16x32_bf16 v[66:69], v[138:141], v[186:189], v[66:69]
	v_mfma_f32_16x16x32_bf16 v[94:97], v[134:137], v[166:169], v[94:97]
	v_mfma_f32_16x16x32_bf16 v[90:93], v[142:145], v[166:169], v[90:93]
	v_mfma_f32_16x16x32_bf16 v[86:89], v[134:137], v[174:177], v[86:89]
	v_mfma_f32_16x16x32_bf16 v[82:85], v[142:145], v[174:177], v[82:85]
	v_mfma_f32_16x16x32_bf16 v[78:81], v[134:137], v[182:185], v[78:81]
	v_mfma_f32_16x16x32_bf16 v[74:77], v[142:145], v[182:185], v[74:77]
	v_mfma_f32_16x16x32_bf16 v[70:73], v[134:137], v[190:193], v[70:73]
	v_mfma_f32_16x16x32_bf16 v[66:69], v[142:145], v[190:193], v[66:69]
	s_setprio 0
	s_setprio 1
	v_mfma_f32_16x16x32_bf16 v[30:33], v[146:149], v[162:165], v[30:33]
	v_mfma_f32_16x16x32_bf16 v[26:29], v[154:157], v[162:165], v[26:29]
	v_mfma_f32_16x16x32_bf16 v[22:25], v[146:149], v[170:173], v[22:25]
	v_mfma_f32_16x16x32_bf16 v[18:21], v[154:157], v[170:173], v[18:21]
	v_mfma_f32_16x16x32_bf16 v[14:17], v[146:149], v[178:181], v[14:17]
	v_mfma_f32_16x16x32_bf16 v[10:13], v[154:157], v[178:181], v[10:13]
	v_mfma_f32_16x16x32_bf16 v[6:9], v[146:149], v[186:189], v[6:9]
	v_mfma_f32_16x16x32_bf16 v[2:5], v[154:157], v[186:189], v[2:5]
	v_mfma_f32_16x16x32_bf16 v[30:33], v[150:153], v[166:169], v[30:33]
	v_mfma_f32_16x16x32_bf16 v[26:29], v[158:161], v[166:169], v[26:29]
	v_mfma_f32_16x16x32_bf16 v[22:25], v[150:153], v[174:177], v[22:25]
	v_mfma_f32_16x16x32_bf16 v[18:21], v[158:161], v[174:177], v[18:21]
	v_mfma_f32_16x16x32_bf16 v[14:17], v[150:153], v[182:185], v[14:17]
	v_mfma_f32_16x16x32_bf16 v[10:13], v[158:161], v[182:185], v[10:13]
	v_mfma_f32_16x16x32_bf16 v[6:9], v[150:153], v[190:193], v[6:9]
	v_mfma_f32_16x16x32_bf16 v[2:5], v[158:161], v[190:193], v[2:5]
	s_setprio 0
	s_barrier
	s_add_i32 s67, s67, 2
	s_add_u32 s62, s62, 0x1c0000
	s_addc_u32 s63, s63, 0
	s_add_u32 s0, s0, 0x440000
	s_addc_u32 s1, s1, 0
	s_cmp_gt_u32 s67, 29
	s_cbranch_scc0 .LBB0_761
	s_and_b64 vcc, exec, s[26:27]
	s_cbranch_vccz .LBB0_764
	s_barrier

.LBB0_903:
	s_mov_b32 m0, s23
	s_nop 0
	global_load_lds_dwordx4 v194, s[100:101]
	s_mov_b32 m0, s31
	s_nop 0
	global_load_lds_dwordx4 v196, s[100:101]
	ds_read_b128 v[146:149], v225
	ds_read_b128 v[150:153], v225 offset:1024
	ds_read_b128 v[154:157], v225 offset:2048
	ds_read_b128 v[158:161], v225 offset:3072
	ds_read_b128 v[130:133], v227
	ds_read_b128 v[134:137], v227 offset:1024
	ds_read_b128 v[138:141], v227 offset:2048
	ds_read_b128 v[142:145], v227 offset:3072
	v_lshl_add_u64 v[234:235], v[210:211], 0, s[62:63]
	s_add_i32 m0, s8, 0xc000
	s_waitcnt lgkmcnt(0)
	ds_read_b128 v[174:177], v228
	ds_read_b128 v[190:193], v228 offset:1024
	ds_read_b128 v[170:173], v228 offset:2048
	ds_read_b128 v[186:189], v228 offset:3072
	ds_read_b128 v[166:169], v228 offset:4096
	ds_read_b128 v[182:185], v228 offset:5120
	ds_read_b128 v[162:165], v228 offset:6144
	ds_read_b128 v[178:181], v228 offset:7168
	global_load_lds_dwordx4 v[234:235], off
	v_lshl_add_u64 v[234:235], v[212:213], 0, s[62:63]
	s_add_i32 m0, s8, 0xe000
	s_nop 0
	global_load_lds_dwordx4 v[234:235], off
	s_waitcnt vmcnt(8)
	s_waitcnt lgkmcnt(0)
	s_barrier
	s_setprio 1
	s_waitcnt lgkmcnt(0)
	v_mfma_f32_16x16x32_bf16 v[126:129], v[146:149], v[174:177], v[126:129]
	v_mfma_f32_16x16x32_bf16 v[122:125], v[154:157], v[174:177], v[122:125]
	v_mfma_f32_16x16x32_bf16 v[118:121], v[146:149], v[170:173], v[118:121]
	v_mfma_f32_16x16x32_bf16 v[114:117], v[154:157], v[170:173], v[114:117]
	v_mfma_f32_16x16x32_bf16 v[110:113], v[146:149], v[166:169], v[110:113]
	v_mfma_f32_16x16x32_bf16 v[106:109], v[154:157], v[166:169], v[106:109]
	v_mfma_f32_16x16x32_bf16 v[102:105], v[146:149], v[162:165], v[102:105]
	v_mfma_f32_16x16x32_bf16 v[98:101], v[154:157], v[162:165], v[98:101]
	v_mfma_f32_16x16x32_bf16 v[126:129], v[150:153], v[190:193], v[126:129]
	v_mfma_f32_16x16x32_bf16 v[122:125], v[158:161], v[190:193], v[122:125]
	v_mfma_f32_16x16x32_bf16 v[118:121], v[150:153], v[186:189], v[118:121]
	v_mfma_f32_16x16x32_bf16 v[114:117], v[158:161], v[186:189], v[114:117]
	v_mfma_f32_16x16x32_bf16 v[110:113], v[150:153], v[182:185], v[110:113]
	v_mfma_f32_16x16x32_bf16 v[106:109], v[158:161], v[182:185], v[106:109]
	v_mfma_f32_16x16x32_bf16 v[102:105], v[150:153], v[178:181], v[102:105]
	v_mfma_f32_16x16x32_bf16 v[98:101], v[158:161], v[178:181], v[98:101]
	s_setprio 0
	s_setprio 1
	v_mfma_f32_16x16x32_bf16 v[94:97], v[130:133], v[174:177], v[94:97]
	v_mfma_f32_16x16x32_bf16 v[90:93], v[138:141], v[174:177], v[90:93]
	v_mfma_f32_16x16x32_bf16 v[86:89], v[130:133], v[170:173], v[86:89]
	v_mfma_f32_16x16x32_bf16 v[82:85], v[138:141], v[170:173], v[82:85]
	v_mfma_f32_16x16x32_bf16 v[78:81], v[130:133], v[166:169], v[78:81]
	v_mfma_f32_16x16x32_bf16 v[74:77], v[138:141], v[166:169], v[74:77]
	v_mfma_f32_16x16x32_bf16 v[70:73], v[130:133], v[162:165], v[70:73]
	v_mfma_f32_16x16x32_bf16 v[66:69], v[138:141], v[162:165], v[66:69]
	v_mfma_f32_16x16x32_bf16 v[94:97], v[134:137], v[190:193], v[94:97]
	v_mfma_f32_16x16x32_bf16 v[90:93], v[142:145], v[190:193], v[90:93]
	v_mfma_f32_16x16x32_bf16 v[86:89], v[134:137], v[186:189], v[86:89]
	v_mfma_f32_16x16x32_bf16 v[82:85], v[142:145], v[186:189], v[82:85]
	v_mfma_f32_16x16x32_bf16 v[78:81], v[134:137], v[182:185], v[78:81]
	v_mfma_f32_16x16x32_bf16 v[74:77], v[142:145], v[182:185], v[74:77]
	v_mfma_f32_16x16x32_bf16 v[70:73], v[134:137], v[178:181], v[70:73]
	v_mfma_f32_16x16x32_bf16 v[66:69], v[142:145], v[178:181], v[66:69]
	s_setprio 0
	s_barrier
	v_cmp_ne_u32_e64 s[42:43], 1, v233
	s_andn2_b64 vcc, exec, s[44:45]
	s_cbranch_vccnz .LBB0_905
	ds_read_b128 v[174:177], v228 offset:16384
	ds_read_b128 v[190:193], v228 offset:17408
	ds_read_b128 v[170:173], v228 offset:18432
	ds_read_b128 v[186:189], v228 offset:19456
	ds_read_b128 v[166:169], v228 offset:20480
	ds_read_b128 v[182:185], v228 offset:21504
	ds_read_b128 v[162:165], v228 offset:22528
	ds_read_b128 v[178:181], v228 offset:23552
.LBB0_905:
	s_add_u32 s68, s0, s62
	s_addc_u32 s69, s1, s63
	s_add_u32 s70, s68, 0x440000
	s_addc_u32 s71, s69, 0
	s_cmp_eq_u32 s62, 0x3fc0000
	s_cselect_b64 s[72:73], -1, 0
	s_and_b64 s[68:69], s[72:73], exec
	s_cselect_b32 s69, s37, s77
	s_cselect_b32 s68, s75, s76
	s_mov_b32 m0, s9
	s_cselect_b32 s71, s35, s71
	s_cselect_b32 s70, s74, s70
	s_add_u32 s80, s68, 0x4000
	global_load_lds_dwordx4 v194, s[68:69]
	s_mov_b32 m0, s10
	s_addc_u32 s81, s69, 0
	global_load_lds_dwordx4 v196, s[68:69]
	s_mov_b32 m0, s11
	s_and_b64 vcc, exec, s[42:43]
	global_load_lds_dwordx4 v194, s[80:81]
	s_mov_b32 m0, s12
	s_nop 0
	global_load_lds_dwordx4 v196, s[80:81]
	s_mov_b64 s[98:99], s[70:71]
	s_waitcnt vmcnt(6)
	s_waitcnt lgkmcnt(0)
	s_barrier
	s_cbranch_vccnz .LBB0_907
	s_setprio 1
	s_waitcnt lgkmcnt(0)
	v_mfma_f32_16x16x32_bf16 v[62:65], v[146:149], v[174:177], v[62:65]
	v_mfma_f32_16x16x32_bf16 v[58:61], v[154:157], v[174:177], v[58:61]
	v_mfma_f32_16x16x32_bf16 v[54:57], v[146:149], v[170:173], v[54:57]
	v_mfma_f32_16x16x32_bf16 v[50:53], v[154:157], v[170:173], v[50:53]
	v_mfma_f32_16x16x32_bf16 v[46:49], v[146:149], v[166:169], v[46:49]
	v_mfma_f32_16x16x32_bf16 v[42:45], v[154:157], v[166:169], v[42:45]
	v_mfma_f32_16x16x32_bf16 v[38:41], v[146:149], v[162:165], v[38:41]
	v_mfma_f32_16x16x32_bf16 v[34:37], v[154:157], v[162:165], v[34:37]
	v_mfma_f32_16x16x32_bf16 v[62:65], v[150:153], v[190:193], v[62:65]
	v_mfma_f32_16x16x32_bf16 v[58:61], v[158:161], v[190:193], v[58:61]
	v_mfma_f32_16x16x32_bf16 v[54:57], v[150:153], v[186:189], v[54:57]
	v_mfma_f32_16x16x32_bf16 v[50:53], v[158:161], v[186:189], v[50:53]
	v_mfma_f32_16x16x32_bf16 v[46:49], v[150:153], v[182:185], v[46:49]
	v_mfma_f32_16x16x32_bf16 v[42:45], v[158:161], v[182:185], v[42:45]
	v_mfma_f32_16x16x32_bf16 v[38:41], v[150:153], v[178:181], v[38:41]
	v_mfma_f32_16x16x32_bf16 v[34:37], v[158:161], v[178:181], v[34:37]
	s_setprio 0
	s_setprio 1
	v_mfma_f32_16x16x32_bf16 v[30:33], v[130:133], v[174:177], v[30:33]
	v_mfma_f32_16x16x32_bf16 v[26:29], v[138:141], v[174:177], v[26:29]
	v_mfma_f32_16x16x32_bf16 v[22:25], v[130:133], v[170:173], v[22:25]
	v_mfma_f32_16x16x32_bf16 v[18:21], v[138:141], v[170:173], v[18:21]
	v_mfma_f32_16x16x32_bf16 v[14:17], v[130:133], v[166:169], v[14:17]
	v_mfma_f32_16x16x32_bf16 v[10:13], v[138:141], v[166:169], v[10:13]
	v_mfma_f32_16x16x32_bf16 v[6:9], v[130:133], v[162:165], v[6:9]
	v_mfma_f32_16x16x32_bf16 v[2:5], v[138:141], v[162:165], v[2:5]
	v_mfma_f32_16x16x32_bf16 v[30:33], v[134:137], v[190:193], v[30:33]
	v_mfma_f32_16x16x32_bf16 v[26:29], v[142:145], v[190:193], v[26:29]
	v_mfma_f32_16x16x32_bf16 v[22:25], v[134:137], v[186:189], v[22:25]
	v_mfma_f32_16x16x32_bf16 v[18:21], v[142:145], v[186:189], v[18:21]
	v_mfma_f32_16x16x32_bf16 v[14:17], v[134:137], v[182:185], v[14:17]
	v_mfma_f32_16x16x32_bf16 v[10:13], v[142:145], v[182:185], v[10:13]
	v_mfma_f32_16x16x32_bf16 v[6:9], v[134:137], v[178:181], v[6:9]
	v_mfma_f32_16x16x32_bf16 v[2:5], v[142:145], v[178:181], v[2:5]
	s_setprio 0
.LBB0_907:
	s_and_b64 vcc, s[40:41], s[72:73]
	v_cndmask_b32_e64 v131, v209, 0, vcc
	v_cndmask_b32_e32 v130, v208, v198, vcc
	v_lshl_add_u64 v[234:235], s[70:71], 0, v[130:131]
	s_barrier
	s_mov_b32 m0, s8
	s_nop 0
	global_load_lds_dwordx4 v194, s[98:99]
	s_mov_b32 m0, s13
	s_nop 0
	global_load_lds_dwordx4 v196, s[98:99]
	v_add_u32_e32 v130, 0x18000, v224
	v_add_u32_e32 v142, 0x1c000, v224
	ds_read_b128 v[146:149], v130
	ds_read_b128 v[150:153], v130 offset:1024
	ds_read_b128 v[154:157], v130 offset:2048
	ds_read_b128 v[158:161], v130 offset:3072
	ds_read_b128 v[130:133], v142
	ds_read_b128 v[134:137], v142 offset:1024
	ds_read_b128 v[138:141], v142 offset:2048
	ds_read_b128 v[142:145], v142 offset:3072
	s_mov_b32 m0, s14
	v_lshl_add_u64 v[236:237], v[234:235], 0, v[194:195]
	s_waitcnt lgkmcnt(0)
	ds_read_b128 v[174:177], v228 offset:32768
	ds_read_b128 v[190:193], v228 offset:33792
	ds_read_b128 v[170:173], v228 offset:34816
	ds_read_b128 v[186:189], v228 offset:35840
	ds_read_b128 v[166:169], v228 offset:36864
	ds_read_b128 v[182:185], v228 offset:37888
	ds_read_b128 v[162:165], v228 offset:38912
	ds_read_b128 v[178:181], v228 offset:39936
	global_load_lds_dwordx4 v[236:237], off
	v_lshl_add_u64 v[234:235], v[234:235], 0, v[196:197]
	s_mov_b32 m0, s15
	s_nop 0
	global_load_lds_dwordx4 v[234:235], off
	s_waitcnt vmcnt(8)
	s_waitcnt lgkmcnt(0)
	s_barrier
	s_setprio 1
	s_waitcnt lgkmcnt(0)
	v_mfma_f32_16x16x32_bf16 v[126:129], v[146:149], v[174:177], v[126:129]
	v_mfma_f32_16x16x32_bf16 v[122:125], v[154:157], v[174:177], v[122:125]
	v_mfma_f32_16x16x32_bf16 v[118:121], v[146:149], v[170:173], v[118:121]
	v_mfma_f32_16x16x32_bf16 v[114:117], v[154:157], v[170:173], v[114:117]
	v_mfma_f32_16x16x32_bf16 v[110:113], v[146:149], v[166:169], v[110:113]
	v_mfma_f32_16x16x32_bf16 v[106:109], v[154:157], v[166:169], v[106:109]
	v_mfma_f32_16x16x32_bf16 v[102:105], v[146:149], v[162:165], v[102:105]
	v_mfma_f32_16x16x32_bf16 v[98:101], v[154:157], v[162:165], v[98:101]
	v_mfma_f32_16x16x32_bf16 v[126:129], v[150:153], v[190:193], v[126:129]
	v_mfma_f32_16x16x32_bf16 v[122:125], v[158:161], v[190:193], v[122:125]
	v_mfma_f32_16x16x32_bf16 v[118:121], v[150:153], v[186:189], v[118:121]
	v_mfma_f32_16x16x32_bf16 v[114:117], v[158:161], v[186:189], v[114:117]
	v_mfma_f32_16x16x32_bf16 v[110:113], v[150:153], v[182:185], v[110:113]
	v_mfma_f32_16x16x32_bf16 v[106:109], v[158:161], v[182:185], v[106:109]
	v_mfma_f32_16x16x32_bf16 v[102:105], v[150:153], v[178:181], v[102:105]
	v_mfma_f32_16x16x32_bf16 v[98:101], v[158:161], v[178:181], v[98:101]
	s_setprio 0
	s_setprio 1
	v_mfma_f32_16x16x32_bf16 v[94:97], v[130:133], v[174:177], v[94:97]
	v_mfma_f32_16x16x32_bf16 v[90:93], v[138:141], v[174:177], v[90:93]
	v_mfma_f32_16x16x32_bf16 v[86:89], v[130:133], v[170:173], v[86:89]
	v_mfma_f32_16x16x32_bf16 v[82:85], v[138:141], v[170:173], v[82:85]
	v_mfma_f32_16x16x32_bf16 v[78:81], v[130:133], v[166:169], v[78:81]
	v_mfma_f32_16x16x32_bf16 v[74:77], v[138:141], v[166:169], v[74:77]
	v_mfma_f32_16x16x32_bf16 v[70:73], v[130:133], v[162:165], v[70:73]
	v_mfma_f32_16x16x32_bf16 v[66:69], v[138:141], v[162:165], v[66:69]
	v_mfma_f32_16x16x32_bf16 v[94:97], v[134:137], v[190:193], v[94:97]
	v_mfma_f32_16x16x32_bf16 v[90:93], v[142:145], v[190:193], v[90:93]
	v_mfma_f32_16x16x32_bf16 v[86:89], v[134:137], v[186:189], v[86:89]
	v_mfma_f32_16x16x32_bf16 v[82:85], v[142:145], v[186:189], v[82:85]
	v_mfma_f32_16x16x32_bf16 v[78:81], v[134:137], v[182:185], v[78:81]
	v_mfma_f32_16x16x32_bf16 v[74:77], v[142:145], v[182:185], v[74:77]
	v_mfma_f32_16x16x32_bf16 v[70:73], v[134:137], v[178:181], v[70:73]
	v_mfma_f32_16x16x32_bf16 v[66:69], v[142:145], v[178:181], v[66:69]
	s_setprio 0
	s_barrier
	s_and_b64 vcc, exec, s[42:43]
	s_cbranch_vccnz .LBB0_909
	ds_read_b128 v[174:177], v228 offset:49152
	ds_read_b128 v[190:193], v228 offset:50176
	ds_read_b128 v[170:173], v228 offset:51200
	ds_read_b128 v[186:189], v228 offset:52224
	ds_read_b128 v[166:169], v228 offset:53248
	ds_read_b128 v[182:185], v228 offset:54272
	ds_read_b128 v[162:165], v228 offset:55296
	ds_read_b128 v[178:181], v228 offset:56320
.LBB0_909:
	s_add_u32 s72, s68, 0xe0000
	s_addc_u32 s73, s69, 0
	s_add_u32 s70, s70, 0x220000
	s_addc_u32 s71, s71, 0
	s_mov_b32 m0, s16
	s_add_u32 s68, s68, 0xe4000
	global_load_lds_dwordx4 v194, s[72:73]
	s_mov_b32 m0, s17
	s_addc_u32 s69, s69, 0
	global_load_lds_dwordx4 v196, s[72:73]
	s_mov_b32 m0, s54
	s_and_b64 vcc, exec, s[42:43]
	global_load_lds_dwordx4 v194, s[68:69]
	s_mov_b32 m0, s55
	s_nop 0
	global_load_lds_dwordx4 v196, s[68:69]
	s_mov_b64 s[100:101], s[70:71]
	s_waitcnt vmcnt(6)
	s_waitcnt lgkmcnt(0)
	s_barrier
	s_cbranch_vccnz .LBB0_902
	s_setprio 1
	s_waitcnt lgkmcnt(0)
	v_mfma_f32_16x16x32_bf16 v[62:65], v[146:149], v[174:177], v[62:65]
	v_mfma_f32_16x16x32_bf16 v[58:61], v[154:157], v[174:177], v[58:61]
	v_mfma_f32_16x16x32_bf16 v[54:57], v[146:149], v[170:173], v[54:57]
	v_mfma_f32_16x16x32_bf16 v[50:53], v[154:157], v[170:173], v[50:53]
	v_mfma_f32_16x16x32_bf16 v[46:49], v[146:149], v[166:169], v[46:49]
	v_mfma_f32_16x16x32_bf16 v[42:45], v[154:157], v[166:169], v[42:45]
	v_mfma_f32_16x16x32_bf16 v[38:41], v[146:149], v[162:165], v[38:41]
	v_mfma_f32_16x16x32_bf16 v[34:37], v[154:157], v[162:165], v[34:37]
	v_mfma_f32_16x16x32_bf16 v[62:65], v[150:153], v[190:193], v[62:65]
	v_mfma_f32_16x16x32_bf16 v[58:61], v[158:161], v[190:193], v[58:61]
	v_mfma_f32_16x16x32_bf16 v[54:57], v[150:153], v[186:189], v[54:57]
	v_mfma_f32_16x16x32_bf16 v[50:53], v[158:161], v[186:189], v[50:53]
	v_mfma_f32_16x16x32_bf16 v[46:49], v[150:153], v[182:185], v[46:49]
	v_mfma_f32_16x16x32_bf16 v[42:45], v[158:161], v[182:185], v[42:45]
	v_mfma_f32_16x16x32_bf16 v[38:41], v[150:153], v[178:181], v[38:41]
	v_mfma_f32_16x16x32_bf16 v[34:37], v[158:161], v[178:181], v[34:37]
	s_setprio 0
	s_setprio 1
	v_mfma_f32_16x16x32_bf16 v[30:33], v[130:133], v[174:177], v[30:33]
	v_mfma_f32_16x16x32_bf16 v[26:29], v[138:141], v[174:177], v[26:29]
	v_mfma_f32_16x16x32_bf16 v[22:25], v[130:133], v[170:173], v[22:25]
	v_mfma_f32_16x16x32_bf16 v[18:21], v[138:141], v[170:173], v[18:21]
	v_mfma_f32_16x16x32_bf16 v[14:17], v[130:133], v[166:169], v[14:17]
	v_mfma_f32_16x16x32_bf16 v[10:13], v[138:141], v[166:169], v[10:13]
	v_mfma_f32_16x16x32_bf16 v[6:9], v[130:133], v[162:165], v[6:9]
	v_mfma_f32_16x16x32_bf16 v[2:5], v[138:141], v[162:165], v[2:5]
	v_mfma_f32_16x16x32_bf16 v[30:33], v[134:137], v[190:193], v[30:33]
	v_mfma_f32_16x16x32_bf16 v[26:29], v[142:145], v[190:193], v[26:29]
	v_mfma_f32_16x16x32_bf16 v[22:25], v[134:137], v[186:189], v[22:25]
	v_mfma_f32_16x16x32_bf16 v[18:21], v[142:145], v[186:189], v[18:21]
	v_mfma_f32_16x16x32_bf16 v[14:17], v[134:137], v[182:185], v[14:17]
	v_mfma_f32_16x16x32_bf16 v[10:13], v[142:145], v[182:185], v[10:13]
	v_mfma_f32_16x16x32_bf16 v[6:9], v[134:137], v[178:181], v[6:9]
	v_mfma_f32_16x16x32_bf16 v[2:5], v[142:145], v[178:181], v[2:5]
	s_setprio 0
	s_branch .LBB0_902

.LBB0_1289:
	s_mov_b32 m0, s27
	s_nop 0
	global_load_lds_dwordx4 v194, s[100:101]
	s_mov_b32 m0, s54
	s_nop 0
	global_load_lds_dwordx4 v196, s[100:101]
	v_add_u32_e32 v142, 0x14000, v229
	ds_read_b128 v[146:149], v230
	ds_read_b128 v[150:153], v230 offset:1024
	ds_read_b128 v[154:157], v230 offset:2048
	ds_read_b128 v[158:161], v230 offset:3072
	ds_read_b128 v[130:133], v142
	ds_read_b128 v[134:137], v142 offset:1024
	ds_read_b128 v[138:141], v142 offset:2048
	ds_read_b128 v[142:145], v142 offset:3072
	v_lshl_add_u64 v[234:235], v[222:223], 0, s[48:49]
	s_add_i32 m0, s8, 0xc000
	s_waitcnt lgkmcnt(0)
	ds_read_b128 v[174:177], v231
	ds_read_b128 v[190:193], v231 offset:1024
	ds_read_b128 v[170:173], v231 offset:2048
	ds_read_b128 v[186:189], v231 offset:3072
	ds_read_b128 v[166:169], v231 offset:4096
	ds_read_b128 v[182:185], v231 offset:5120
	ds_read_b128 v[162:165], v231 offset:6144
	ds_read_b128 v[178:181], v231 offset:7168
	global_load_lds_dwordx4 v[234:235], off
	v_lshl_add_u64 v[234:235], v[224:225], 0, s[48:49]
	s_add_i32 m0, s8, 0xe000
	s_nop 0
	global_load_lds_dwordx4 v[234:235], off
	s_waitcnt vmcnt(8)
	s_waitcnt lgkmcnt(0)
	s_barrier
	s_setprio 1
	s_waitcnt lgkmcnt(0)
	v_mfma_f32_16x16x32_bf16 v[126:129], v[146:149], v[174:177], v[126:129]
	v_mfma_f32_16x16x32_bf16 v[122:125], v[154:157], v[174:177], v[122:125]
	v_mfma_f32_16x16x32_bf16 v[118:121], v[146:149], v[170:173], v[118:121]
	v_mfma_f32_16x16x32_bf16 v[110:113], v[154:157], v[170:173], v[110:113]
	v_mfma_f32_16x16x32_bf16 v[102:105], v[146:149], v[166:169], v[102:105]
	v_mfma_f32_16x16x32_bf16 v[94:97], v[154:157], v[166:169], v[94:97]
	v_mfma_f32_16x16x32_bf16 v[86:89], v[146:149], v[162:165], v[86:89]
	v_mfma_f32_16x16x32_bf16 v[78:81], v[154:157], v[162:165], v[78:81]
	v_mfma_f32_16x16x32_bf16 v[126:129], v[150:153], v[190:193], v[126:129]
	v_mfma_f32_16x16x32_bf16 v[122:125], v[158:161], v[190:193], v[122:125]
	v_mfma_f32_16x16x32_bf16 v[118:121], v[150:153], v[186:189], v[118:121]
	v_mfma_f32_16x16x32_bf16 v[110:113], v[158:161], v[186:189], v[110:113]
	v_mfma_f32_16x16x32_bf16 v[102:105], v[150:153], v[182:185], v[102:105]
	v_mfma_f32_16x16x32_bf16 v[94:97], v[158:161], v[182:185], v[94:97]
	v_mfma_f32_16x16x32_bf16 v[86:89], v[150:153], v[178:181], v[86:89]
	v_mfma_f32_16x16x32_bf16 v[78:81], v[158:161], v[178:181], v[78:81]
	s_setprio 0
	s_setprio 1
	v_mfma_f32_16x16x32_bf16 v[114:117], v[130:133], v[174:177], v[114:117]
	v_mfma_f32_16x16x32_bf16 v[106:109], v[138:141], v[174:177], v[106:109]
	v_mfma_f32_16x16x32_bf16 v[98:101], v[130:133], v[170:173], v[98:101]
	v_mfma_f32_16x16x32_bf16 v[90:93], v[138:141], v[170:173], v[90:93]
	v_mfma_f32_16x16x32_bf16 v[82:85], v[130:133], v[166:169], v[82:85]
	v_mfma_f32_16x16x32_bf16 v[74:77], v[138:141], v[166:169], v[74:77]
	v_mfma_f32_16x16x32_bf16 v[70:73], v[130:133], v[162:165], v[70:73]
	v_mfma_f32_16x16x32_bf16 v[66:69], v[138:141], v[162:165], v[66:69]
	v_mfma_f32_16x16x32_bf16 v[114:117], v[134:137], v[190:193], v[114:117]
	v_mfma_f32_16x16x32_bf16 v[106:109], v[142:145], v[190:193], v[106:109]
	v_mfma_f32_16x16x32_bf16 v[98:101], v[134:137], v[186:189], v[98:101]
	v_mfma_f32_16x16x32_bf16 v[90:93], v[142:145], v[186:189], v[90:93]
	v_mfma_f32_16x16x32_bf16 v[82:85], v[134:137], v[182:185], v[82:85]
	v_mfma_f32_16x16x32_bf16 v[74:77], v[142:145], v[182:185], v[74:77]
	v_mfma_f32_16x16x32_bf16 v[70:73], v[134:137], v[178:181], v[70:73]
	v_mfma_f32_16x16x32_bf16 v[66:69], v[142:145], v[178:181], v[66:69]
	s_setprio 0
	s_barrier
	v_cndmask_b32_e64 v233, 0, 1, s[40:41]
	v_cmp_ne_u32_e64 s[42:43], 1, v233
	s_andn2_b64 vcc, exec, s[40:41]
	s_cbranch_vccnz .LBB0_1291
	ds_read_b128 v[174:177], v231 offset:16384
	ds_read_b128 v[190:193], v231 offset:17408
	ds_read_b128 v[170:173], v231 offset:18432
	ds_read_b128 v[186:189], v231 offset:19456
	ds_read_b128 v[166:169], v231 offset:20480
	ds_read_b128 v[182:185], v231 offset:21504
	ds_read_b128 v[162:165], v231 offset:22528
	ds_read_b128 v[178:181], v231 offset:23552
.LBB0_1291:
	s_add_u32 s52, s36, s48
	s_addc_u32 s53, s37, s49
	s_add_u32 s56, s52, 0x440000
	s_addc_u32 s57, s53, 0
	s_cmp_eq_u32 s48, 0x3fc0000
	s_cselect_b64 s[58:59], -1, 0
	s_and_b64 s[52:53], s[58:59], exec
	s_cselect_b32 s53, s31, s63
	s_cselect_b32 s52, s61, s62
	s_mov_b32 m0, s9
	s_cselect_b32 s57, s19, s57
	s_cselect_b32 s56, s29, s56
	s_add_u32 s68, s52, 0x4000
	global_load_lds_dwordx4 v194, s[52:53]
	s_mov_b32 m0, s10
	s_addc_u32 s69, s53, 0
	global_load_lds_dwordx4 v196, s[52:53]
	s_mov_b32 m0, s11
	s_and_b64 vcc, exec, s[42:43]
	global_load_lds_dwordx4 v194, s[68:69]
	s_mov_b32 m0, s12
	s_nop 0
	global_load_lds_dwordx4 v196, s[68:69]
	s_mov_b64 s[98:99], s[56:57]
	s_waitcnt vmcnt(6)
	s_waitcnt lgkmcnt(0)
	s_barrier
	s_cbranch_vccnz .LBB0_1293
	s_setprio 1
	s_waitcnt lgkmcnt(0)
	v_mfma_f32_16x16x32_bf16 v[62:65], v[146:149], v[174:177], v[62:65]
	v_mfma_f32_16x16x32_bf16 v[58:61], v[154:157], v[174:177], v[58:61]
	v_mfma_f32_16x16x32_bf16 v[46:49], v[146:149], v[170:173], v[46:49]
	v_mfma_f32_16x16x32_bf16 v[42:45], v[154:157], v[170:173], v[42:45]
	v_mfma_f32_16x16x32_bf16 v[30:33], v[146:149], v[166:169], v[30:33]
	v_mfma_f32_16x16x32_bf16 v[26:29], v[154:157], v[166:169], v[26:29]
	v_mfma_f32_16x16x32_bf16 v[14:17], v[146:149], v[162:165], v[14:17]
	v_mfma_f32_16x16x32_bf16 v[10:13], v[154:157], v[162:165], v[10:13]
	v_mfma_f32_16x16x32_bf16 v[62:65], v[150:153], v[190:193], v[62:65]
	v_mfma_f32_16x16x32_bf16 v[58:61], v[158:161], v[190:193], v[58:61]
	v_mfma_f32_16x16x32_bf16 v[46:49], v[150:153], v[186:189], v[46:49]
	v_mfma_f32_16x16x32_bf16 v[42:45], v[158:161], v[186:189], v[42:45]
	v_mfma_f32_16x16x32_bf16 v[30:33], v[150:153], v[182:185], v[30:33]
	v_mfma_f32_16x16x32_bf16 v[26:29], v[158:161], v[182:185], v[26:29]
	v_mfma_f32_16x16x32_bf16 v[14:17], v[150:153], v[178:181], v[14:17]
	v_mfma_f32_16x16x32_bf16 v[10:13], v[158:161], v[178:181], v[10:13]
	s_setprio 0
	s_setprio 1
	v_mfma_f32_16x16x32_bf16 v[54:57], v[130:133], v[174:177], v[54:57]
	v_mfma_f32_16x16x32_bf16 v[50:53], v[138:141], v[174:177], v[50:53]
	v_mfma_f32_16x16x32_bf16 v[38:41], v[130:133], v[170:173], v[38:41]
	v_mfma_f32_16x16x32_bf16 v[34:37], v[138:141], v[170:173], v[34:37]
	v_mfma_f32_16x16x32_bf16 v[22:25], v[130:133], v[166:169], v[22:25]
	v_mfma_f32_16x16x32_bf16 v[18:21], v[138:141], v[166:169], v[18:21]
	v_mfma_f32_16x16x32_bf16 v[6:9], v[130:133], v[162:165], v[6:9]
	v_mfma_f32_16x16x32_bf16 v[2:5], v[138:141], v[162:165], v[2:5]
	v_mfma_f32_16x16x32_bf16 v[54:57], v[134:137], v[190:193], v[54:57]
	v_mfma_f32_16x16x32_bf16 v[50:53], v[142:145], v[190:193], v[50:53]
	v_mfma_f32_16x16x32_bf16 v[38:41], v[134:137], v[186:189], v[38:41]
	v_mfma_f32_16x16x32_bf16 v[34:37], v[142:145], v[186:189], v[34:37]
	v_mfma_f32_16x16x32_bf16 v[22:25], v[134:137], v[182:185], v[22:25]
	v_mfma_f32_16x16x32_bf16 v[18:21], v[142:145], v[182:185], v[18:21]
	v_mfma_f32_16x16x32_bf16 v[6:9], v[134:137], v[178:181], v[6:9]
	v_mfma_f32_16x16x32_bf16 v[2:5], v[142:145], v[178:181], v[2:5]
	s_setprio 0
.LBB0_1293:
	s_and_b64 vcc, s[34:35], s[58:59]
	v_cndmask_b32_e64 v131, v221, 0, vcc
	v_cndmask_b32_e32 v130, v220, v198, vcc
	v_lshl_add_u64 v[234:235], s[56:57], 0, v[130:131]
	s_barrier
	s_mov_b32 m0, s8
	s_nop 0
	global_load_lds_dwordx4 v194, s[98:99]
	s_mov_b32 m0, s13
	s_nop 0
	global_load_lds_dwordx4 v196, s[98:99]
	v_add_u32_e32 v130, 0x18000, v229
	v_add_u32_e32 v142, 0x1c000, v229
	ds_read_b128 v[146:149], v130
	ds_read_b128 v[150:153], v130 offset:1024
	ds_read_b128 v[154:157], v130 offset:2048
	ds_read_b128 v[158:161], v130 offset:3072
	ds_read_b128 v[130:133], v142
	ds_read_b128 v[134:137], v142 offset:1024
	ds_read_b128 v[138:141], v142 offset:2048
	ds_read_b128 v[142:145], v142 offset:3072
	s_mov_b32 m0, s14
	v_lshl_add_u64 v[236:237], v[234:235], 0, v[194:195]
	s_waitcnt lgkmcnt(0)
	ds_read_b128 v[174:177], v231 offset:32768
	ds_read_b128 v[190:193], v231 offset:33792
	ds_read_b128 v[170:173], v231 offset:34816
	ds_read_b128 v[186:189], v231 offset:35840
	ds_read_b128 v[166:169], v231 offset:36864
	ds_read_b128 v[182:185], v231 offset:37888
	ds_read_b128 v[162:165], v231 offset:38912
	ds_read_b128 v[178:181], v231 offset:39936
	global_load_lds_dwordx4 v[236:237], off
	v_lshl_add_u64 v[234:235], v[234:235], 0, v[196:197]
	s_mov_b32 m0, s15
	s_nop 0
	global_load_lds_dwordx4 v[234:235], off
	s_waitcnt vmcnt(8)
	s_waitcnt lgkmcnt(0)
	s_barrier
	s_setprio 1
	s_waitcnt lgkmcnt(0)
	v_mfma_f32_16x16x32_bf16 v[126:129], v[146:149], v[174:177], v[126:129]
	v_mfma_f32_16x16x32_bf16 v[122:125], v[154:157], v[174:177], v[122:125]
	v_mfma_f32_16x16x32_bf16 v[118:121], v[146:149], v[170:173], v[118:121]
	v_mfma_f32_16x16x32_bf16 v[110:113], v[154:157], v[170:173], v[110:113]
	v_mfma_f32_16x16x32_bf16 v[102:105], v[146:149], v[166:169], v[102:105]
	v_mfma_f32_16x16x32_bf16 v[94:97], v[154:157], v[166:169], v[94:97]
	v_mfma_f32_16x16x32_bf16 v[86:89], v[146:149], v[162:165], v[86:89]
	v_mfma_f32_16x16x32_bf16 v[78:81], v[154:157], v[162:165], v[78:81]
	v_mfma_f32_16x16x32_bf16 v[126:129], v[150:153], v[190:193], v[126:129]
	v_mfma_f32_16x16x32_bf16 v[122:125], v[158:161], v[190:193], v[122:125]
	v_mfma_f32_16x16x32_bf16 v[118:121], v[150:153], v[186:189], v[118:121]
	v_mfma_f32_16x16x32_bf16 v[110:113], v[158:161], v[186:189], v[110:113]
	v_mfma_f32_16x16x32_bf16 v[102:105], v[150:153], v[182:185], v[102:105]
	v_mfma_f32_16x16x32_bf16 v[94:97], v[158:161], v[182:185], v[94:97]
	v_mfma_f32_16x16x32_bf16 v[86:89], v[150:153], v[178:181], v[86:89]
	v_mfma_f32_16x16x32_bf16 v[78:81], v[158:161], v[178:181], v[78:81]
	s_setprio 0
	s_setprio 1
	v_mfma_f32_16x16x32_bf16 v[114:117], v[130:133], v[174:177], v[114:117]
	v_mfma_f32_16x16x32_bf16 v[106:109], v[138:141], v[174:177], v[106:109]
	v_mfma_f32_16x16x32_bf16 v[98:101], v[130:133], v[170:173], v[98:101]
	v_mfma_f32_16x16x32_bf16 v[90:93], v[138:141], v[170:173], v[90:93]
	v_mfma_f32_16x16x32_bf16 v[82:85], v[130:133], v[166:169], v[82:85]
	v_mfma_f32_16x16x32_bf16 v[74:77], v[138:141], v[166:169], v[74:77]
	v_mfma_f32_16x16x32_bf16 v[70:73], v[130:133], v[162:165], v[70:73]
	v_mfma_f32_16x16x32_bf16 v[66:69], v[138:141], v[162:165], v[66:69]
	v_mfma_f32_16x16x32_bf16 v[114:117], v[134:137], v[190:193], v[114:117]
	v_mfma_f32_16x16x32_bf16 v[106:109], v[142:145], v[190:193], v[106:109]
	v_mfma_f32_16x16x32_bf16 v[98:101], v[134:137], v[186:189], v[98:101]
	v_mfma_f32_16x16x32_bf16 v[90:93], v[142:145], v[186:189], v[90:93]
	v_mfma_f32_16x16x32_bf16 v[82:85], v[134:137], v[182:185], v[82:85]
	v_mfma_f32_16x16x32_bf16 v[74:77], v[142:145], v[182:185], v[74:77]
	v_mfma_f32_16x16x32_bf16 v[70:73], v[134:137], v[178:181], v[70:73]
	v_mfma_f32_16x16x32_bf16 v[66:69], v[142:145], v[178:181], v[66:69]
	s_setprio 0
	s_barrier
	s_and_b64 vcc, exec, s[42:43]
	s_cbranch_vccnz .LBB0_1295
	ds_read_b128 v[174:177], v231 offset:49152
	ds_read_b128 v[190:193], v231 offset:50176
	ds_read_b128 v[170:173], v231 offset:51200
	ds_read_b128 v[186:189], v231 offset:52224
	ds_read_b128 v[166:169], v231 offset:53248
	ds_read_b128 v[182:185], v231 offset:54272
	ds_read_b128 v[162:165], v231 offset:55296
	ds_read_b128 v[178:181], v231 offset:56320
.LBB0_1295:
	s_add_u32 s58, s52, 0x40000
	s_addc_u32 s59, s53, 0
	s_add_u32 s56, s56, 0x220000
	s_addc_u32 s57, s57, 0
	s_mov_b32 m0, s16
	s_add_u32 s52, s52, 0x44000
	global_load_lds_dwordx4 v194, s[58:59]
	s_mov_b32 m0, s17
	s_addc_u32 s53, s53, 0
	global_load_lds_dwordx4 v196, s[58:59]
	s_mov_b32 m0, s55
	s_and_b64 vcc, exec, s[42:43]
	global_load_lds_dwordx4 v194, s[52:53]
	s_mov_b32 m0, s60
	s_nop 0
	global_load_lds_dwordx4 v196, s[52:53]
	s_mov_b64 s[100:101], s[56:57]
	s_waitcnt vmcnt(6)
	s_waitcnt lgkmcnt(0)
	s_barrier
	s_cbranch_vccnz .LBB0_1288
	s_setprio 1
	s_waitcnt lgkmcnt(0)
	v_mfma_f32_16x16x32_bf16 v[62:65], v[146:149], v[174:177], v[62:65]
	v_mfma_f32_16x16x32_bf16 v[58:61], v[154:157], v[174:177], v[58:61]
	v_mfma_f32_16x16x32_bf16 v[46:49], v[146:149], v[170:173], v[46:49]
	v_mfma_f32_16x16x32_bf16 v[42:45], v[154:157], v[170:173], v[42:45]
	v_mfma_f32_16x16x32_bf16 v[30:33], v[146:149], v[166:169], v[30:33]
	v_mfma_f32_16x16x32_bf16 v[26:29], v[154:157], v[166:169], v[26:29]
	v_mfma_f32_16x16x32_bf16 v[14:17], v[146:149], v[162:165], v[14:17]
	v_mfma_f32_16x16x32_bf16 v[10:13], v[154:157], v[162:165], v[10:13]
	v_mfma_f32_16x16x32_bf16 v[62:65], v[150:153], v[190:193], v[62:65]
	v_mfma_f32_16x16x32_bf16 v[58:61], v[158:161], v[190:193], v[58:61]
	v_mfma_f32_16x16x32_bf16 v[46:49], v[150:153], v[186:189], v[46:49]
	v_mfma_f32_16x16x32_bf16 v[42:45], v[158:161], v[186:189], v[42:45]
	v_mfma_f32_16x16x32_bf16 v[30:33], v[150:153], v[182:185], v[30:33]
	v_mfma_f32_16x16x32_bf16 v[26:29], v[158:161], v[182:185], v[26:29]
	v_mfma_f32_16x16x32_bf16 v[14:17], v[150:153], v[178:181], v[14:17]
	v_mfma_f32_16x16x32_bf16 v[10:13], v[158:161], v[178:181], v[10:13]
	s_setprio 0
	s_setprio 1
	v_mfma_f32_16x16x32_bf16 v[54:57], v[130:133], v[174:177], v[54:57]
	v_mfma_f32_16x16x32_bf16 v[50:53], v[138:141], v[174:177], v[50:53]
	v_mfma_f32_16x16x32_bf16 v[38:41], v[130:133], v[170:173], v[38:41]
	v_mfma_f32_16x16x32_bf16 v[34:37], v[138:141], v[170:173], v[34:37]
	v_mfma_f32_16x16x32_bf16 v[22:25], v[130:133], v[166:169], v[22:25]
	v_mfma_f32_16x16x32_bf16 v[18:21], v[138:141], v[166:169], v[18:21]
	v_mfma_f32_16x16x32_bf16 v[6:9], v[130:133], v[162:165], v[6:9]
	v_mfma_f32_16x16x32_bf16 v[2:5], v[138:141], v[162:165], v[2:5]
	v_mfma_f32_16x16x32_bf16 v[54:57], v[134:137], v[190:193], v[54:57]
	v_mfma_f32_16x16x32_bf16 v[50:53], v[142:145], v[190:193], v[50:53]
	v_mfma_f32_16x16x32_bf16 v[38:41], v[134:137], v[186:189], v[38:41]
	v_mfma_f32_16x16x32_bf16 v[34:37], v[142:145], v[186:189], v[34:37]
	v_mfma_f32_16x16x32_bf16 v[22:25], v[134:137], v[182:185], v[22:25]
	v_mfma_f32_16x16x32_bf16 v[18:21], v[142:145], v[182:185], v[18:21]
	v_mfma_f32_16x16x32_bf16 v[6:9], v[134:137], v[178:181], v[6:9]
	v_mfma_f32_16x16x32_bf16 v[2:5], v[142:145], v[178:181], v[2:5]
	s_setprio 0
	s_branch .LBB0_1288

.LBB0_1612:
	s_mov_b32 m0, s54
	s_nop 0
	global_load_lds_dwordx4 v194, s[100:101]
	s_mov_b32 m0, s55
	s_nop 0
	global_load_lds_dwordx4 v196, s[100:101]
	v_add_u32_e32 v1, 0x10000, v232
	ds_read_b128 v[146:149], v1
	ds_read_b128 v[150:153], v1 offset:1024
	ds_read_b128 v[154:157], v1 offset:2048
	ds_read_b128 v[158:161], v1 offset:3072
	v_add_u32_e32 v1, 0x14000, v232
	ds_read_b128 v[130:133], v1
	ds_read_b128 v[134:137], v1 offset:1024
	ds_read_b128 v[138:141], v1 offset:2048
	ds_read_b128 v[142:145], v1 offset:3072
	v_lshl_add_u64 v[236:237], v[226:227], 0, s[48:49]
	s_add_i32 m0, s9, 0xc000
	s_waitcnt lgkmcnt(0)
	ds_read_b128 v[174:177], v233
	ds_read_b128 v[190:193], v233 offset:1024
	ds_read_b128 v[170:173], v233 offset:2048
	ds_read_b128 v[186:189], v233 offset:3072
	ds_read_b128 v[166:169], v233 offset:4096
	ds_read_b128 v[182:185], v233 offset:5120
	ds_read_b128 v[162:165], v233 offset:6144
	ds_read_b128 v[178:181], v233 offset:7168
	global_load_lds_dwordx4 v[236:237], off
	v_lshl_add_u64 v[236:237], v[228:229], 0, s[48:49]
	s_add_i32 m0, s9, 0xe000
	s_nop 0
	global_load_lds_dwordx4 v[236:237], off
	s_waitcnt vmcnt(8)
	s_waitcnt lgkmcnt(0)
	s_barrier
	s_setprio 1
	s_waitcnt lgkmcnt(0)
	v_mfma_f32_16x16x32_bf16 v[126:129], v[146:149], v[174:177], v[126:129]
	v_mfma_f32_16x16x32_bf16 v[122:125], v[154:157], v[174:177], v[122:125]
	v_mfma_f32_16x16x32_bf16 v[118:121], v[146:149], v[170:173], v[118:121]
	v_mfma_f32_16x16x32_bf16 v[110:113], v[154:157], v[170:173], v[110:113]
	v_mfma_f32_16x16x32_bf16 v[102:105], v[146:149], v[166:169], v[102:105]
	v_mfma_f32_16x16x32_bf16 v[94:97], v[154:157], v[166:169], v[94:97]
	v_mfma_f32_16x16x32_bf16 v[86:89], v[146:149], v[162:165], v[86:89]
	v_mfma_f32_16x16x32_bf16 v[78:81], v[154:157], v[162:165], v[78:81]
	v_mfma_f32_16x16x32_bf16 v[126:129], v[150:153], v[190:193], v[126:129]
	v_mfma_f32_16x16x32_bf16 v[122:125], v[158:161], v[190:193], v[122:125]
	v_mfma_f32_16x16x32_bf16 v[118:121], v[150:153], v[186:189], v[118:121]
	v_mfma_f32_16x16x32_bf16 v[110:113], v[158:161], v[186:189], v[110:113]
	v_mfma_f32_16x16x32_bf16 v[102:105], v[150:153], v[182:185], v[102:105]
	v_mfma_f32_16x16x32_bf16 v[94:97], v[158:161], v[182:185], v[94:97]
	v_mfma_f32_16x16x32_bf16 v[86:89], v[150:153], v[178:181], v[86:89]
	v_mfma_f32_16x16x32_bf16 v[78:81], v[158:161], v[178:181], v[78:81]
	s_setprio 0
	s_setprio 1
	v_mfma_f32_16x16x32_bf16 v[114:117], v[130:133], v[174:177], v[114:117]
	v_mfma_f32_16x16x32_bf16 v[106:109], v[138:141], v[174:177], v[106:109]
	v_mfma_f32_16x16x32_bf16 v[98:101], v[130:133], v[170:173], v[98:101]
	v_mfma_f32_16x16x32_bf16 v[90:93], v[138:141], v[170:173], v[90:93]
	v_mfma_f32_16x16x32_bf16 v[82:85], v[130:133], v[166:169], v[82:85]
	v_mfma_f32_16x16x32_bf16 v[74:77], v[138:141], v[166:169], v[74:77]
	v_mfma_f32_16x16x32_bf16 v[70:73], v[130:133], v[162:165], v[70:73]
	v_mfma_f32_16x16x32_bf16 v[66:69], v[138:141], v[162:165], v[66:69]
	v_mfma_f32_16x16x32_bf16 v[114:117], v[134:137], v[190:193], v[114:117]
	v_mfma_f32_16x16x32_bf16 v[106:109], v[142:145], v[190:193], v[106:109]
	v_mfma_f32_16x16x32_bf16 v[98:101], v[134:137], v[186:189], v[98:101]
	v_mfma_f32_16x16x32_bf16 v[90:93], v[142:145], v[186:189], v[90:93]
	v_mfma_f32_16x16x32_bf16 v[82:85], v[134:137], v[182:185], v[82:85]
	v_mfma_f32_16x16x32_bf16 v[74:77], v[142:145], v[182:185], v[74:77]
	v_mfma_f32_16x16x32_bf16 v[70:73], v[134:137], v[178:181], v[70:73]
	v_mfma_f32_16x16x32_bf16 v[66:69], v[142:145], v[178:181], v[66:69]
	s_setprio 0
	s_barrier
	v_cndmask_b32_e64 v1, 0, 1, s[40:41]
	v_cmp_ne_u32_e64 s[42:43], 1, v1
	s_andn2_b64 vcc, exec, s[40:41]
	s_cbranch_vccnz .LBB0_1614
	ds_read_b128 v[174:177], v233 offset:16384
	ds_read_b128 v[190:193], v233 offset:17408
	ds_read_b128 v[170:173], v233 offset:18432
	ds_read_b128 v[186:189], v233 offset:19456
	ds_read_b128 v[166:169], v233 offset:20480
	ds_read_b128 v[182:185], v233 offset:21504
	ds_read_b128 v[162:165], v233 offset:22528
	ds_read_b128 v[178:181], v233 offset:23552
.LBB0_1614:
	s_add_u32 s50, s46, s48
	s_addc_u32 s51, s47, s49
	s_add_u32 s52, s50, 0x440000
	s_addc_u32 s53, s51, 0
	s_cmp_eq_u32 s48, 0x3fc0000
	s_cselect_b64 s[56:57], -1, 0
	s_and_b64 s[50:51], s[56:57], exec
	s_cselect_b32 s51, s31, s61
	s_cselect_b32 s50, s35, s60
	s_mov_b32 m0, s10
	s_cselect_b32 s53, s19, s53
	s_cselect_b32 s52, s20, s52
	s_add_u32 s68, s50, 0x4000
	global_load_lds_dwordx4 v194, s[50:51]
	s_mov_b32 m0, s11
	s_addc_u32 s69, s51, 0
	global_load_lds_dwordx4 v196, s[50:51]
	s_mov_b32 m0, s12
	s_and_b64 vcc, exec, s[42:43]
	global_load_lds_dwordx4 v194, s[68:69]
	s_mov_b32 m0, s13
	s_nop 0
	global_load_lds_dwordx4 v196, s[68:69]
	s_mov_b64 s[98:99], s[52:53]
	s_waitcnt vmcnt(6)
	s_waitcnt lgkmcnt(0)
	s_barrier
	s_cbranch_vccnz .LBB0_1616
	s_setprio 1
	s_waitcnt lgkmcnt(0)
	v_mfma_f32_16x16x32_bf16 v[62:65], v[146:149], v[174:177], v[62:65]
	v_mfma_f32_16x16x32_bf16 v[58:61], v[154:157], v[174:177], v[58:61]
	v_mfma_f32_16x16x32_bf16 v[46:49], v[146:149], v[170:173], v[46:49]
	v_mfma_f32_16x16x32_bf16 v[42:45], v[154:157], v[170:173], v[42:45]
	v_mfma_f32_16x16x32_bf16 v[30:33], v[146:149], v[166:169], v[30:33]
	v_mfma_f32_16x16x32_bf16 v[26:29], v[154:157], v[166:169], v[26:29]
	v_mfma_f32_16x16x32_bf16 v[14:17], v[146:149], v[162:165], v[14:17]
	v_mfma_f32_16x16x32_bf16 v[10:13], v[154:157], v[162:165], v[10:13]
	v_mfma_f32_16x16x32_bf16 v[62:65], v[150:153], v[190:193], v[62:65]
	v_mfma_f32_16x16x32_bf16 v[58:61], v[158:161], v[190:193], v[58:61]
	v_mfma_f32_16x16x32_bf16 v[46:49], v[150:153], v[186:189], v[46:49]
	v_mfma_f32_16x16x32_bf16 v[42:45], v[158:161], v[186:189], v[42:45]
	v_mfma_f32_16x16x32_bf16 v[30:33], v[150:153], v[182:185], v[30:33]
	v_mfma_f32_16x16x32_bf16 v[26:29], v[158:161], v[182:185], v[26:29]
	v_mfma_f32_16x16x32_bf16 v[14:17], v[150:153], v[178:181], v[14:17]
	v_mfma_f32_16x16x32_bf16 v[10:13], v[158:161], v[178:181], v[10:13]
	s_setprio 0
	s_setprio 1
	v_mfma_f32_16x16x32_bf16 v[54:57], v[130:133], v[174:177], v[54:57]
	v_mfma_f32_16x16x32_bf16 v[50:53], v[138:141], v[174:177], v[50:53]
	v_mfma_f32_16x16x32_bf16 v[38:41], v[130:133], v[170:173], v[38:41]
	v_mfma_f32_16x16x32_bf16 v[34:37], v[138:141], v[170:173], v[34:37]
	v_mfma_f32_16x16x32_bf16 v[22:25], v[130:133], v[166:169], v[22:25]
	v_mfma_f32_16x16x32_bf16 v[18:21], v[138:141], v[166:169], v[18:21]
	v_mfma_f32_16x16x32_bf16 v[6:9], v[130:133], v[162:165], v[6:9]
	v_mfma_f32_16x16x32_bf16 v[2:5], v[138:141], v[162:165], v[2:5]
	v_mfma_f32_16x16x32_bf16 v[54:57], v[134:137], v[190:193], v[54:57]
	v_mfma_f32_16x16x32_bf16 v[50:53], v[142:145], v[190:193], v[50:53]
	v_mfma_f32_16x16x32_bf16 v[38:41], v[134:137], v[186:189], v[38:41]
	v_mfma_f32_16x16x32_bf16 v[34:37], v[142:145], v[186:189], v[34:37]
	v_mfma_f32_16x16x32_bf16 v[22:25], v[134:137], v[182:185], v[22:25]
	v_mfma_f32_16x16x32_bf16 v[18:21], v[142:145], v[182:185], v[18:21]
	v_mfma_f32_16x16x32_bf16 v[6:9], v[134:137], v[178:181], v[6:9]
	v_mfma_f32_16x16x32_bf16 v[2:5], v[142:145], v[178:181], v[2:5]
	s_setprio 0
.LBB0_1616:
	s_and_b64 vcc, s[38:39], s[56:57]
	v_cndmask_b32_e64 v131, v225, 0, vcc
	v_cndmask_b32_e32 v130, v224, v198, vcc
	v_lshl_add_u64 v[236:237], s[52:53], 0, v[130:131]
	s_barrier
	s_mov_b32 m0, s9
	s_nop 0
	global_load_lds_dwordx4 v194, s[98:99]
	s_mov_b32 m0, s14
	s_nop 0
	global_load_lds_dwordx4 v196, s[98:99]
	v_add_u32_e32 v1, 0x18000, v232
	ds_read_b128 v[146:149], v1
	ds_read_b128 v[150:153], v1 offset:1024
	ds_read_b128 v[154:157], v1 offset:2048
	ds_read_b128 v[158:161], v1 offset:3072
	v_add_u32_e32 v1, 0x1c000, v232
	ds_read_b128 v[130:133], v1
	ds_read_b128 v[134:137], v1 offset:1024
	ds_read_b128 v[138:141], v1 offset:2048
	ds_read_b128 v[142:145], v1 offset:3072
	s_mov_b32 m0, s15
	v_lshl_add_u64 v[238:239], v[236:237], 0, v[194:195]
	s_waitcnt lgkmcnt(0)
	ds_read_b128 v[174:177], v233 offset:32768
	ds_read_b128 v[190:193], v233 offset:33792
	ds_read_b128 v[170:173], v233 offset:34816
	ds_read_b128 v[186:189], v233 offset:35840
	ds_read_b128 v[166:169], v233 offset:36864
	ds_read_b128 v[182:185], v233 offset:37888
	ds_read_b128 v[162:165], v233 offset:38912
	ds_read_b128 v[178:181], v233 offset:39936
	global_load_lds_dwordx4 v[238:239], off
	v_lshl_add_u64 v[236:237], v[236:237], 0, v[196:197]
	s_mov_b32 m0, s16
	s_nop 0
	global_load_lds_dwordx4 v[236:237], off
	s_waitcnt vmcnt(8)
	s_waitcnt lgkmcnt(0)
	s_barrier
	s_setprio 1
	s_waitcnt lgkmcnt(0)
	v_mfma_f32_16x16x32_bf16 v[126:129], v[146:149], v[174:177], v[126:129]
	v_mfma_f32_16x16x32_bf16 v[122:125], v[154:157], v[174:177], v[122:125]
	v_mfma_f32_16x16x32_bf16 v[118:121], v[146:149], v[170:173], v[118:121]
	v_mfma_f32_16x16x32_bf16 v[110:113], v[154:157], v[170:173], v[110:113]
	v_mfma_f32_16x16x32_bf16 v[102:105], v[146:149], v[166:169], v[102:105]
	v_mfma_f32_16x16x32_bf16 v[94:97], v[154:157], v[166:169], v[94:97]
	v_mfma_f32_16x16x32_bf16 v[86:89], v[146:149], v[162:165], v[86:89]
	v_mfma_f32_16x16x32_bf16 v[78:81], v[154:157], v[162:165], v[78:81]
	v_mfma_f32_16x16x32_bf16 v[126:129], v[150:153], v[190:193], v[126:129]
	v_mfma_f32_16x16x32_bf16 v[122:125], v[158:161], v[190:193], v[122:125]
	v_mfma_f32_16x16x32_bf16 v[118:121], v[150:153], v[186:189], v[118:121]
	v_mfma_f32_16x16x32_bf16 v[110:113], v[158:161], v[186:189], v[110:113]
	v_mfma_f32_16x16x32_bf16 v[102:105], v[150:153], v[182:185], v[102:105]
	v_mfma_f32_16x16x32_bf16 v[94:97], v[158:161], v[182:185], v[94:97]
	v_mfma_f32_16x16x32_bf16 v[86:89], v[150:153], v[178:181], v[86:89]
	v_mfma_f32_16x16x32_bf16 v[78:81], v[158:161], v[178:181], v[78:81]
	s_setprio 0
	s_setprio 1
	v_mfma_f32_16x16x32_bf16 v[114:117], v[130:133], v[174:177], v[114:117]
	v_mfma_f32_16x16x32_bf16 v[106:109], v[138:141], v[174:177], v[106:109]
	v_mfma_f32_16x16x32_bf16 v[98:101], v[130:133], v[170:173], v[98:101]
	v_mfma_f32_16x16x32_bf16 v[90:93], v[138:141], v[170:173], v[90:93]
	v_mfma_f32_16x16x32_bf16 v[82:85], v[130:133], v[166:169], v[82:85]
	v_mfma_f32_16x16x32_bf16 v[74:77], v[138:141], v[166:169], v[74:77]
	v_mfma_f32_16x16x32_bf16 v[70:73], v[130:133], v[162:165], v[70:73]
	v_mfma_f32_16x16x32_bf16 v[66:69], v[138:141], v[162:165], v[66:69]
	v_mfma_f32_16x16x32_bf16 v[114:117], v[134:137], v[190:193], v[114:117]
	v_mfma_f32_16x16x32_bf16 v[106:109], v[142:145], v[190:193], v[106:109]
	v_mfma_f32_16x16x32_bf16 v[98:101], v[134:137], v[186:189], v[98:101]
	v_mfma_f32_16x16x32_bf16 v[90:93], v[142:145], v[186:189], v[90:93]
	v_mfma_f32_16x16x32_bf16 v[82:85], v[134:137], v[182:185], v[82:85]
	v_mfma_f32_16x16x32_bf16 v[74:77], v[142:145], v[182:185], v[74:77]
	v_mfma_f32_16x16x32_bf16 v[70:73], v[134:137], v[178:181], v[70:73]
	v_mfma_f32_16x16x32_bf16 v[66:69], v[142:145], v[178:181], v[66:69]
	s_setprio 0
	s_barrier
	s_and_b64 vcc, exec, s[42:43]
	s_cbranch_vccnz .LBB0_1618
	ds_read_b128 v[174:177], v233 offset:49152
	ds_read_b128 v[190:193], v233 offset:50176
	ds_read_b128 v[170:173], v233 offset:51200
	ds_read_b128 v[186:189], v233 offset:52224
	ds_read_b128 v[166:169], v233 offset:53248
	ds_read_b128 v[182:185], v233 offset:54272
	ds_read_b128 v[162:165], v233 offset:55296
	ds_read_b128 v[178:181], v233 offset:56320
.LBB0_1618:
	s_add_u32 s56, s50, 0x40000
	s_addc_u32 s57, s51, 0
	s_add_u32 s52, s52, 0x220000
	s_addc_u32 s53, s53, 0
	s_mov_b32 m0, s17
	s_add_u32 s50, s50, 0x44000
	global_load_lds_dwordx4 v194, s[56:57]
	s_mov_b32 m0, s29
	s_addc_u32 s51, s51, 0
	global_load_lds_dwordx4 v196, s[56:57]
	s_mov_b32 m0, s58
	s_and_b64 vcc, exec, s[42:43]
	global_load_lds_dwordx4 v194, s[50:51]
	s_mov_b32 m0, s59
	s_nop 0
	global_load_lds_dwordx4 v196, s[50:51]
	s_mov_b64 s[100:101], s[52:53]
	s_waitcnt vmcnt(6)
	s_waitcnt lgkmcnt(0)
	s_barrier
	s_cbranch_vccnz .LBB0_1611
	s_setprio 1
	s_waitcnt lgkmcnt(0)
	v_mfma_f32_16x16x32_bf16 v[62:65], v[146:149], v[174:177], v[62:65]
	v_mfma_f32_16x16x32_bf16 v[58:61], v[154:157], v[174:177], v[58:61]
	v_mfma_f32_16x16x32_bf16 v[46:49], v[146:149], v[170:173], v[46:49]
	v_mfma_f32_16x16x32_bf16 v[42:45], v[154:157], v[170:173], v[42:45]
	v_mfma_f32_16x16x32_bf16 v[30:33], v[146:149], v[166:169], v[30:33]
	v_mfma_f32_16x16x32_bf16 v[26:29], v[154:157], v[166:169], v[26:29]
	v_mfma_f32_16x16x32_bf16 v[14:17], v[146:149], v[162:165], v[14:17]
	v_mfma_f32_16x16x32_bf16 v[10:13], v[154:157], v[162:165], v[10:13]
	v_mfma_f32_16x16x32_bf16 v[62:65], v[150:153], v[190:193], v[62:65]
	v_mfma_f32_16x16x32_bf16 v[58:61], v[158:161], v[190:193], v[58:61]
	v_mfma_f32_16x16x32_bf16 v[46:49], v[150:153], v[186:189], v[46:49]
	v_mfma_f32_16x16x32_bf16 v[42:45], v[158:161], v[186:189], v[42:45]
	v_mfma_f32_16x16x32_bf16 v[30:33], v[150:153], v[182:185], v[30:33]
	v_mfma_f32_16x16x32_bf16 v[26:29], v[158:161], v[182:185], v[26:29]
	v_mfma_f32_16x16x32_bf16 v[14:17], v[150:153], v[178:181], v[14:17]
	v_mfma_f32_16x16x32_bf16 v[10:13], v[158:161], v[178:181], v[10:13]
	s_setprio 0
	s_setprio 1
	v_mfma_f32_16x16x32_bf16 v[54:57], v[130:133], v[174:177], v[54:57]
	v_mfma_f32_16x16x32_bf16 v[50:53], v[138:141], v[174:177], v[50:53]
	v_mfma_f32_16x16x32_bf16 v[38:41], v[130:133], v[170:173], v[38:41]
	v_mfma_f32_16x16x32_bf16 v[34:37], v[138:141], v[170:173], v[34:37]
	v_mfma_f32_16x16x32_bf16 v[22:25], v[130:133], v[166:169], v[22:25]
	v_mfma_f32_16x16x32_bf16 v[18:21], v[138:141], v[166:169], v[18:21]
	v_mfma_f32_16x16x32_bf16 v[6:9], v[130:133], v[162:165], v[6:9]
	v_mfma_f32_16x16x32_bf16 v[2:5], v[138:141], v[162:165], v[2:5]
	v_mfma_f32_16x16x32_bf16 v[54:57], v[134:137], v[190:193], v[54:57]
	v_mfma_f32_16x16x32_bf16 v[50:53], v[142:145], v[190:193], v[50:53]
	v_mfma_f32_16x16x32_bf16 v[38:41], v[134:137], v[186:189], v[38:41]
	v_mfma_f32_16x16x32_bf16 v[34:37], v[142:145], v[186:189], v[34:37]
	v_mfma_f32_16x16x32_bf16 v[22:25], v[134:137], v[182:185], v[22:25]
	v_mfma_f32_16x16x32_bf16 v[18:21], v[142:145], v[182:185], v[18:21]
	v_mfma_f32_16x16x32_bf16 v[6:9], v[134:137], v[178:181], v[6:9]
	v_mfma_f32_16x16x32_bf16 v[2:5], v[142:145], v[178:181], v[2:5]
	s_setprio 0
	s_branch .LBB0_1611
